# deferred generation check polled by wave 0 only (the ALIGN rendezvous gates the other seven waves); they keep their next-unit prefetch in flight
# speedup vs baseline: 1.0064x; 1.0064x over previous
; #define PG8_STAGE(bufoff, gbase, voff) do { _Pragma("unroll") for (int _i = 0; _i < 2; ++_i) \
;         __builtin_amdgcn_global_load_lds((const unsigned*)((const char*)(gbase) + (voff)[_i]), (PG8_LAS unsigned*)(lds + (bufoff) + ldsw + _i * 8192), 16, 0, 0); } while (0)
; #define PG8_LDA(dst, b, h) do { _Pragma("unroll") for (int m = 0; m < 4; ++m) _Pragma("unroll") for (int k = 0; k < 2; ++k) dst[m][k] = *(const PG8_LAS bf16x8*)(lds + PG8_SA(b, h) + aoff + m * 2048 + k * 1024); } while (0)
; #define PG8_LDB(dst, b, h) do { _Pragma("unroll") for (int n = 0; n < 2; ++n) _Pragma("unroll") for (int k = 0; k < 2; ++k) dst[n][k] = *(const PG8_LAS bf16x8*)(lds + PG8_SB(b, h) + boff + n * 2048 + k * 1024); } while (0)
; #define PG8_MMA(ai, bj, At, Bt) do { __builtin_amdgcn_s_setprio(1); _Pragma("unroll") for (int m = 0; m < 4; ++m) _Pragma("unroll") for (int n = 0; n < 2; ++n) _Pragma("unroll") for (int k = 0; k < 2; ++k) \
;         acc[ai][bj][m][n] = __builtin_amdgcn_mfma_f32_16x16x32_bf16(Bt[n][k], At[m][k], acc[ai][bj][m][n], 0, 0, 0); __builtin_amdgcn_s_setprio(0); } while (0)
; #define PG8_WAIT_V(n) asm volatile("s_waitcnt vmcnt(" #n ")" ::: "memory")
; #define PG8_WAIT_L(n) asm volatile("s_waitcnt lgkmcnt(" #n ")" ::: "memory")
; #define PG8_BAR __builtin_amdgcn_s_barrier()
; #define PG8_SCHED __builtin_amdgcn_sched_barrier(0)
; template <class Epi, class Sched, bool ALIGN_EPI = false, bool SP2 = false>
; __device__ __forceinline__ void gemm_phase(PG8_LAS unsigned char* lds, const Gemm g, const Sched& S, const Epi& E) {
;     ...
;             PG8_LDB(B0, 0, 0); PG8_LDB(B1, 0, 1); PG8_SCHED; PG8_LDA(At, 0, 0); PG8_STAGE(PG8_SA(1, 1), a1 + hstep, voffA);
;             PG8_WAIT_V(8); PG8_WAIT_L(0); PG8_BAR; PG8_MMA(0, 0, At, B0); PG8_MMA(0, 1, At, B1); PG8_BAR; PG8_SCHED;
;             PG8_LDA(At, 0, 1); PG8_STAGE(PG8_SB(0, 0), b2, voffB); PG8_STAGE(PG8_SB(0, 1), b2 + hstep, voffB); PG8_STAGE(PG8_SA(0, 0), a2, voffA);
;             PG8_WAIT_V(8); PG8_WAIT_L(0); PG8_BAR; PG8_MMA(1, 0, At, B0); PG8_MMA(1, 1, At, B1); PG8_BAR; PG8_SCHED;
.LBB0_414:
	ds_read_b128 v[146:149], v165
	ds_read_b128 v[150:153], v165 offset:1024
	ds_read_b128 v[154:157], v165 offset:2048
	ds_read_b128 v[168:171], v165 offset:3072
	ds_read_b128 v[172:175], v166
	ds_read_b128 v[176:179], v166 offset:1024
	ds_read_b128 v[180:183], v166 offset:2048
	ds_read_b128 v[184:187], v166 offset:3072
	s_add_u32 s52, s20, 0xfffc0080
	s_addc_u32 s53, s21, -1
	s_cmp_eq_u32 s84, 12
	s_cselect_b32 s55, s43, s53
	s_cselect_b32 s54, s78, s52
	s_cselect_b32 s53, s19, s81
	s_cselect_b32 s52, s79, s80
	s_add_i32 m0, s35, 0xc000
	ds_read_b128 v[188:191], v167
	ds_read_b128 v[192:195], v167 offset:1024
	ds_read_b128 v[198:201], v167 offset:2048
	ds_read_b128 v[202:205], v167 offset:3072
	ds_read_b128 v[206:209], v167 offset:4096
	ds_read_b128 v[210:213], v167 offset:5120
	ds_read_b128 v[214:217], v167 offset:6144
	ds_read_b128 v[218:221], v167 offset:7168
	global_load_lds_dwordx4 v138, s[20:21]
	s_add_i32 m0, s35, 0xe000
	s_nop 0
	global_load_lds_dwordx4 v140, s[20:21]
	s_waitcnt vmcnt(8)
	s_waitcnt lgkmcnt(0)
	s_barrier
	v_mfma_f32_16x16x32_bf16 v[124:127], v[146:149], v[188:191], v[124:127]
	v_mfma_f32_16x16x32_bf16 v[120:123], v[154:157], v[188:191], v[120:123]
	v_mfma_f32_16x16x32_bf16 v[108:111], v[146:149], v[198:201], v[108:111]
	v_mfma_f32_16x16x32_bf16 v[104:107], v[154:157], v[198:201], v[104:107]
	v_mfma_f32_16x16x32_bf16 v[92:95], v[146:149], v[206:209], v[92:95]
	v_mfma_f32_16x16x32_bf16 v[88:91], v[154:157], v[206:209], v[88:91]
	v_mfma_f32_16x16x32_bf16 v[76:79], v[146:149], v[214:217], v[76:79]
	v_mfma_f32_16x16x32_bf16 v[72:75], v[154:157], v[214:217], v[72:75]
	v_mfma_f32_16x16x32_bf16 v[124:127], v[150:153], v[192:195], v[124:127]
	v_mfma_f32_16x16x32_bf16 v[120:123], v[168:171], v[192:195], v[120:123]
	v_mfma_f32_16x16x32_bf16 v[108:111], v[150:153], v[202:205], v[108:111]
	v_mfma_f32_16x16x32_bf16 v[104:107], v[168:171], v[202:205], v[104:107]
	v_mfma_f32_16x16x32_bf16 v[92:95], v[150:153], v[210:213], v[92:95]
	v_mfma_f32_16x16x32_bf16 v[88:91], v[168:171], v[210:213], v[88:91]
	v_mfma_f32_16x16x32_bf16 v[76:79], v[150:153], v[218:221], v[76:79]
	v_mfma_f32_16x16x32_bf16 v[72:75], v[168:171], v[218:221], v[72:75]
	v_mfma_f32_16x16x32_bf16 v[116:119], v[172:175], v[188:191], v[116:119]
	v_mfma_f32_16x16x32_bf16 v[112:115], v[180:183], v[188:191], v[112:115]
	v_mfma_f32_16x16x32_bf16 v[100:103], v[172:175], v[198:201], v[100:103]
	v_mfma_f32_16x16x32_bf16 v[96:99], v[180:183], v[198:201], v[96:99]
	v_mfma_f32_16x16x32_bf16 v[84:87], v[172:175], v[206:209], v[84:87]
	v_mfma_f32_16x16x32_bf16 v[80:83], v[180:183], v[206:209], v[80:83]
	v_mfma_f32_16x16x32_bf16 v[68:71], v[172:175], v[214:217], v[68:71]
	v_mfma_f32_16x16x32_bf16 v[64:67], v[180:183], v[214:217], v[64:67]
	v_mfma_f32_16x16x32_bf16 v[116:119], v[176:179], v[192:195], v[116:119]
	v_mfma_f32_16x16x32_bf16 v[112:115], v[184:187], v[192:195], v[112:115]
	v_mfma_f32_16x16x32_bf16 v[100:103], v[176:179], v[202:205], v[100:103]
	v_mfma_f32_16x16x32_bf16 v[96:99], v[184:187], v[202:205], v[96:99]
	v_mfma_f32_16x16x32_bf16 v[84:87], v[176:179], v[210:213], v[84:87]
	v_mfma_f32_16x16x32_bf16 v[80:83], v[184:187], v[210:213], v[80:83]
	v_mfma_f32_16x16x32_bf16 v[68:71], v[176:179], v[218:221], v[68:71]
	v_mfma_f32_16x16x32_bf16 v[64:67], v[184:187], v[218:221], v[64:67]
	s_barrier
	s_add_i32 s85, s72, s63
	s_add_u32 s98, s52, s8
	s_addc_u32 s99, s53, s9
	s_add_u32 s100, s54, s8
	s_addc_u32 s101, s55, s9
	s_mov_b32 m0, s85
	ds_read_b128 v[188:191], v167 offset:16384
	ds_read_b128 v[192:195], v167 offset:17408
	ds_read_b128 v[198:201], v167 offset:18432
	ds_read_b128 v[202:205], v167 offset:19456
	ds_read_b128 v[206:209], v167 offset:20480
	ds_read_b128 v[210:213], v167 offset:21504
	ds_read_b128 v[214:217], v167 offset:22528
	ds_read_b128 v[218:221], v167 offset:23552
	global_load_lds_dwordx4 v132, s[52:53]
	s_add_i32 m0, s85, 0x2000
	s_add_u32 s86, s52, 0x40000
	s_addc_u32 s87, s53, 0
	s_add_i32 s85, s73, s63
	global_load_lds_dwordx4 v128, s[52:53]
	s_mov_b32 m0, s85
	s_nop 0
	global_load_lds_dwordx4 v132, s[86:87]
	s_add_i32 m0, s85, 0x2000
	s_nop 0
	global_load_lds_dwordx4 v128, s[86:87]
	s_mov_b32 m0, s35
	s_nop 0
	global_load_lds_dwordx4 v134, s[54:55]
	s_mov_b32 m0, s65
	s_nop 0
	global_load_lds_dwordx4 v130, s[54:55]
	s_waitcnt vmcnt(8)
	s_waitcnt lgkmcnt(0)
	s_barrier
	v_mfma_f32_16x16x32_bf16 v[60:63], v[146:149], v[188:191], v[60:63]
	v_mfma_f32_16x16x32_bf16 v[56:59], v[154:157], v[188:191], v[56:59]
	v_mfma_f32_16x16x32_bf16 v[44:47], v[146:149], v[198:201], v[44:47]
	v_mfma_f32_16x16x32_bf16 v[40:43], v[154:157], v[198:201], v[40:43]
	v_mfma_f32_16x16x32_bf16 v[28:31], v[146:149], v[206:209], v[28:31]
	v_mfma_f32_16x16x32_bf16 v[24:27], v[154:157], v[206:209], v[24:27]
	v_mfma_f32_16x16x32_bf16 v[12:15], v[146:149], v[214:217], v[12:15]
	v_mfma_f32_16x16x32_bf16 v[8:11], v[154:157], v[214:217], v[8:11]
	v_mfma_f32_16x16x32_bf16 v[60:63], v[150:153], v[192:195], v[60:63]
	v_mfma_f32_16x16x32_bf16 v[56:59], v[168:171], v[192:195], v[56:59]
	v_mfma_f32_16x16x32_bf16 v[44:47], v[150:153], v[202:205], v[44:47]
	v_mfma_f32_16x16x32_bf16 v[40:43], v[168:171], v[202:205], v[40:43]
	v_mfma_f32_16x16x32_bf16 v[28:31], v[150:153], v[210:213], v[28:31]
	v_mfma_f32_16x16x32_bf16 v[24:27], v[168:171], v[210:213], v[24:27]
	v_mfma_f32_16x16x32_bf16 v[12:15], v[150:153], v[218:221], v[12:15]
	v_mfma_f32_16x16x32_bf16 v[8:11], v[168:171], v[218:221], v[8:11]
	v_mfma_f32_16x16x32_bf16 v[52:55], v[172:175], v[188:191], v[52:55]
	v_mfma_f32_16x16x32_bf16 v[48:51], v[180:183], v[188:191], v[48:51]
	v_mfma_f32_16x16x32_bf16 v[36:39], v[172:175], v[198:201], v[36:39]
	v_mfma_f32_16x16x32_bf16 v[32:35], v[180:183], v[198:201], v[32:35]
	v_mfma_f32_16x16x32_bf16 v[20:23], v[172:175], v[206:209], v[20:23]
	v_mfma_f32_16x16x32_bf16 v[16:19], v[180:183], v[206:209], v[16:19]
	v_mfma_f32_16x16x32_bf16 v[4:7], v[172:175], v[214:217], v[4:7]
	v_mfma_f32_16x16x32_bf16 v[0:3], v[180:183], v[214:217], v[0:3]
	v_mfma_f32_16x16x32_bf16 v[52:55], v[176:179], v[192:195], v[52:55]
	v_mfma_f32_16x16x32_bf16 v[48:51], v[184:187], v[192:195], v[48:51]
	v_mfma_f32_16x16x32_bf16 v[36:39], v[176:179], v[202:205], v[36:39]
	v_mfma_f32_16x16x32_bf16 v[32:35], v[184:187], v[202:205], v[32:35]
	v_mfma_f32_16x16x32_bf16 v[20:23], v[176:179], v[210:213], v[20:23]
	v_mfma_f32_16x16x32_bf16 v[16:19], v[184:187], v[210:213], v[16:19]
	v_mfma_f32_16x16x32_bf16 v[4:7], v[176:179], v[218:221], v[4:7]
	v_mfma_f32_16x16x32_bf16 v[0:3], v[184:187], v[218:221], v[0:3]
	s_barrier
; #define PG8_STAGE(bufoff, gbase, voff) do { _Pragma("unroll") for (int _i = 0; _i < 2; ++_i) \
;         __builtin_amdgcn_global_load_lds((const unsigned*)((const char*)(gbase) + (voff)[_i]), (PG8_LAS unsigned*)(lds + (bufoff) + ldsw + _i * 8192), 16, 0, 0); } while (0)
; #define PG8_LDA(dst, b, h) do { _Pragma("unroll") for (int m = 0; m < 4; ++m) _Pragma("unroll") for (int k = 0; k < 2; ++k) dst[m][k] = *(const PG8_LAS bf16x8*)(lds + PG8_SA(b, h) + aoff + m * 2048 + k * 1024); } while (0)
; #define PG8_LDB(dst, b, h) do { _Pragma("unroll") for (int n = 0; n < 2; ++n) _Pragma("unroll") for (int k = 0; k < 2; ++k) dst[n][k] = *(const PG8_LAS bf16x8*)(lds + PG8_SB(b, h) + boff + n * 2048 + k * 1024); } while (0)
; #define PG8_MMA(ai, bj, At, Bt) do { __builtin_amdgcn_s_setprio(1); _Pragma("unroll") for (int m = 0; m < 4; ++m) _Pragma("unroll") for (int n = 0; n < 2; ++n) _Pragma("unroll") for (int k = 0; k < 2; ++k) \
;         acc[ai][bj][m][n] = __builtin_amdgcn_mfma_f32_16x16x32_bf16(Bt[n][k], At[m][k], acc[ai][bj][m][n], 0, 0, 0); __builtin_amdgcn_s_setprio(0); } while (0)
; #define PG8_WAIT_V(n) asm volatile("s_waitcnt vmcnt(" #n ")" ::: "memory")
; #define PG8_WAIT_L(n) asm volatile("s_waitcnt lgkmcnt(" #n ")" ::: "memory")
; #define PG8_BAR __builtin_amdgcn_s_barrier()
; #define PG8_SCHED __builtin_amdgcn_sched_barrier(0)
; template <class Epi, class Sched, bool ALIGN_EPI = false, bool SP2 = false>
; __device__ __forceinline__ void gemm_phase(PG8_LAS unsigned char* lds, const Gemm g, const Sched& S, const Epi& E) {
;     ...
;         for (int t = 0; t < nt; t += 2) {
;     ...
;             PG8_LDB(B0, 1, 0); PG8_LDB(B1, 1, 1); PG8_SCHED; PG8_LDA(At, 1, 0); PG8_STAGE(PG8_SA(0, 1), a2 + hstep, voffA);
;             PG8_WAIT_V(8); PG8_WAIT_L(0); PG8_BAR; PG8_MMA(0, 0, At, B0); PG8_MMA(0, 1, At, B1); PG8_BAR; PG8_SCHED;
;             PG8_LDA(At, 1, 1); PG8_STAGE(PG8_SB(1, 0), b3, voffB); PG8_STAGE(PG8_SB(1, 1), b3 + hstep, voffB); PG8_STAGE(PG8_SA(1, 0), a3, voffA);
;             PG8_WAIT_V(8); PG8_WAIT_L(0); PG8_BAR; PG8_MMA(1, 0, At, B0); PG8_MMA(1, 1, At, B1); PG8_BAR; PG8_SCHED;
	s_add_i32 s85, 0, 0x18000
	v_add_u32_e32 v136, s85, v161
	s_add_i32 s86, 0, 0x1c000
	ds_read_b128 v[146:149], v136
	ds_read_b128 v[150:153], v136 offset:1024
	ds_read_b128 v[154:157], v136 offset:2048
	ds_read_b128 v[168:171], v136 offset:3072
	v_add_u32_e32 v136, s86, v161
	ds_read_b128 v[172:175], v136
	ds_read_b128 v[176:179], v136 offset:1024
	ds_read_b128 v[180:183], v136 offset:2048
	ds_read_b128 v[184:187], v136 offset:3072
	s_add_u32 s54, s54, 0x40000
	s_addc_u32 s55, s55, 0
	s_mov_b32 m0, s66
	ds_read_b128 v[188:191], v167 offset:32768
	ds_read_b128 v[192:195], v167 offset:33792
	ds_read_b128 v[198:201], v167 offset:34816
	ds_read_b128 v[202:205], v167 offset:35840
	ds_read_b128 v[206:209], v167 offset:36864
	ds_read_b128 v[210:213], v167 offset:37888
	ds_read_b128 v[214:217], v167 offset:38912
	ds_read_b128 v[218:221], v167 offset:39936
	global_load_lds_dwordx4 v134, s[54:55]
	s_mov_b32 m0, s67
	s_nop 0
	global_load_lds_dwordx4 v130, s[54:55]
	s_waitcnt vmcnt(8)
	s_waitcnt lgkmcnt(0)
	s_barrier
	v_mfma_f32_16x16x32_bf16 v[124:127], v[146:149], v[188:191], v[124:127]
	v_mfma_f32_16x16x32_bf16 v[120:123], v[154:157], v[188:191], v[120:123]
	v_mfma_f32_16x16x32_bf16 v[108:111], v[146:149], v[198:201], v[108:111]
	v_mfma_f32_16x16x32_bf16 v[104:107], v[154:157], v[198:201], v[104:107]
	v_mfma_f32_16x16x32_bf16 v[92:95], v[146:149], v[206:209], v[92:95]
	v_mfma_f32_16x16x32_bf16 v[88:91], v[154:157], v[206:209], v[88:91]
	v_mfma_f32_16x16x32_bf16 v[76:79], v[146:149], v[214:217], v[76:79]
	v_mfma_f32_16x16x32_bf16 v[72:75], v[154:157], v[214:217], v[72:75]
	v_mfma_f32_16x16x32_bf16 v[124:127], v[150:153], v[192:195], v[124:127]
	v_mfma_f32_16x16x32_bf16 v[120:123], v[168:171], v[192:195], v[120:123]
	v_mfma_f32_16x16x32_bf16 v[108:111], v[150:153], v[202:205], v[108:111]
	v_mfma_f32_16x16x32_bf16 v[104:107], v[168:171], v[202:205], v[104:107]
	v_mfma_f32_16x16x32_bf16 v[92:95], v[150:153], v[210:213], v[92:95]
	v_mfma_f32_16x16x32_bf16 v[88:91], v[168:171], v[210:213], v[88:91]
	v_mfma_f32_16x16x32_bf16 v[76:79], v[150:153], v[218:221], v[76:79]
	v_mfma_f32_16x16x32_bf16 v[72:75], v[168:171], v[218:221], v[72:75]
	v_mfma_f32_16x16x32_bf16 v[116:119], v[172:175], v[188:191], v[116:119]
	v_mfma_f32_16x16x32_bf16 v[112:115], v[180:183], v[188:191], v[112:115]
	v_mfma_f32_16x16x32_bf16 v[100:103], v[172:175], v[198:201], v[100:103]
	v_mfma_f32_16x16x32_bf16 v[96:99], v[180:183], v[198:201], v[96:99]
	v_mfma_f32_16x16x32_bf16 v[84:87], v[172:175], v[206:209], v[84:87]
	v_mfma_f32_16x16x32_bf16 v[80:83], v[180:183], v[206:209], v[80:83]
	v_mfma_f32_16x16x32_bf16 v[68:71], v[172:175], v[214:217], v[68:71]
	v_mfma_f32_16x16x32_bf16 v[64:67], v[180:183], v[214:217], v[64:67]
	v_mfma_f32_16x16x32_bf16 v[116:119], v[176:179], v[192:195], v[116:119]
	v_mfma_f32_16x16x32_bf16 v[112:115], v[184:187], v[192:195], v[112:115]
	v_mfma_f32_16x16x32_bf16 v[100:103], v[176:179], v[202:205], v[100:103]
	v_mfma_f32_16x16x32_bf16 v[96:99], v[184:187], v[202:205], v[96:99]
	v_mfma_f32_16x16x32_bf16 v[84:87], v[176:179], v[210:213], v[84:87]
	v_mfma_f32_16x16x32_bf16 v[80:83], v[184:187], v[210:213], v[80:83]
	v_mfma_f32_16x16x32_bf16 v[68:71], v[176:179], v[218:221], v[68:71]
	v_mfma_f32_16x16x32_bf16 v[64:67], v[184:187], v[218:221], v[64:67]
	s_barrier
	s_add_i32 s54, s85, s63
	s_mov_b32 m0, s54
	ds_read_b128 v[188:191], v167 offset:49152
	ds_read_b128 v[192:195], v167 offset:50176
	ds_read_b128 v[198:201], v167 offset:51200
	ds_read_b128 v[202:205], v167 offset:52224
	ds_read_b128 v[206:209], v167 offset:53248
	ds_read_b128 v[210:213], v167 offset:54272
	ds_read_b128 v[214:217], v167 offset:55296
	ds_read_b128 v[218:221], v167 offset:56320
	global_load_lds_dwordx4 v132, s[98:99]
	s_add_i32 m0, s54, 0x2000
	s_add_u32 s52, s52, 0x40080
	s_addc_u32 s53, s53, 0
	s_add_i32 s54, s86, s63
	global_load_lds_dwordx4 v128, s[98:99]
	s_mov_b32 m0, s54
	s_nop 0
	global_load_lds_dwordx4 v132, s[52:53]
	s_add_i32 m0, s54, 0x2000
	s_nop 0
	global_load_lds_dwordx4 v128, s[52:53]
	s_mov_b32 m0, s69
	s_nop 0
	global_load_lds_dwordx4 v134, s[100:101]
	s_mov_b32 m0, s70
	s_nop 0
	global_load_lds_dwordx4 v130, s[100:101]
	s_waitcnt vmcnt(8)
	s_waitcnt lgkmcnt(0)
	s_barrier
	v_mfma_f32_16x16x32_bf16 v[60:63], v[146:149], v[188:191], v[60:63]
	v_mfma_f32_16x16x32_bf16 v[56:59], v[154:157], v[188:191], v[56:59]
	v_mfma_f32_16x16x32_bf16 v[44:47], v[146:149], v[198:201], v[44:47]
	v_mfma_f32_16x16x32_bf16 v[40:43], v[154:157], v[198:201], v[40:43]
	v_mfma_f32_16x16x32_bf16 v[28:31], v[146:149], v[206:209], v[28:31]
	v_mfma_f32_16x16x32_bf16 v[24:27], v[154:157], v[206:209], v[24:27]
	v_mfma_f32_16x16x32_bf16 v[12:15], v[146:149], v[214:217], v[12:15]
	v_mfma_f32_16x16x32_bf16 v[8:11], v[154:157], v[214:217], v[8:11]
	v_mfma_f32_16x16x32_bf16 v[60:63], v[150:153], v[192:195], v[60:63]
	v_mfma_f32_16x16x32_bf16 v[56:59], v[168:171], v[192:195], v[56:59]
	v_mfma_f32_16x16x32_bf16 v[44:47], v[150:153], v[202:205], v[44:47]
	v_mfma_f32_16x16x32_bf16 v[40:43], v[168:171], v[202:205], v[40:43]
	v_mfma_f32_16x16x32_bf16 v[28:31], v[150:153], v[210:213], v[28:31]
	v_mfma_f32_16x16x32_bf16 v[24:27], v[168:171], v[210:213], v[24:27]
	v_mfma_f32_16x16x32_bf16 v[12:15], v[150:153], v[218:221], v[12:15]
	v_mfma_f32_16x16x32_bf16 v[8:11], v[168:171], v[218:221], v[8:11]
	v_mfma_f32_16x16x32_bf16 v[52:55], v[172:175], v[188:191], v[52:55]
	v_mfma_f32_16x16x32_bf16 v[48:51], v[180:183], v[188:191], v[48:51]
	v_mfma_f32_16x16x32_bf16 v[36:39], v[172:175], v[198:201], v[36:39]
	v_mfma_f32_16x16x32_bf16 v[32:35], v[180:183], v[198:201], v[32:35]
	v_mfma_f32_16x16x32_bf16 v[20:23], v[172:175], v[206:209], v[20:23]
	v_mfma_f32_16x16x32_bf16 v[16:19], v[180:183], v[206:209], v[16:19]
	v_mfma_f32_16x16x32_bf16 v[4:7], v[172:175], v[214:217], v[4:7]
	v_mfma_f32_16x16x32_bf16 v[0:3], v[180:183], v[214:217], v[0:3]
	v_mfma_f32_16x16x32_bf16 v[52:55], v[176:179], v[192:195], v[52:55]
	v_mfma_f32_16x16x32_bf16 v[48:51], v[184:187], v[192:195], v[48:51]
	v_mfma_f32_16x16x32_bf16 v[36:39], v[176:179], v[202:205], v[36:39]
	v_mfma_f32_16x16x32_bf16 v[32:35], v[184:187], v[202:205], v[32:35]
	v_mfma_f32_16x16x32_bf16 v[20:23], v[176:179], v[210:213], v[20:23]
	v_mfma_f32_16x16x32_bf16 v[16:19], v[184:187], v[210:213], v[16:19]
	v_mfma_f32_16x16x32_bf16 v[4:7], v[176:179], v[218:221], v[4:7]
	v_mfma_f32_16x16x32_bf16 v[0:3], v[184:187], v[218:221], v[0:3]
	s_barrier
	s_add_i32 s84, s84, 2
	s_add_u32 s20, s20, 0x100
	s_addc_u32 s21, s21, 0
	s_add_u32 s80, s80, 0x100
	s_addc_u32 s81, s81, 0
	s_cmp_gt_u32 s84, 13
	s_cbranch_scc0 .LBB0_414
	v_readlane_b32 s101, v249, 49
	s_nop 3
	s_cmp_eq_u32 s101, 0
	s_cbranch_scc1 .Ldw_done_0
	v_readlane_b32 s100, v249, 18
	s_nop 3
	s_cmp_lg_u32 s100, 0
	s_cbranch_scc1 .Ldw_ok_0
	s_add_u32 s98, s28, 0x183500
	s_addc_u32 s99, s29, 0
	v_mov_b32_e32 v251, 0
	s_mov_b32 s100, 0

; #define PG8_STAGE(bufoff, gbase, voff) do { _Pragma("unroll") for (int _i = 0; _i < 2; ++_i) \
;         __builtin_amdgcn_global_load_lds((const unsigned*)((const char*)(gbase) + (voff)[_i]), (PG8_LAS unsigned*)(lds + (bufoff) + ldsw + _i * 8192), 16, 0, 0); } while (0)
; #define PG8_LDA(dst, b, h) do { _Pragma("unroll") for (int m = 0; m < 4; ++m) _Pragma("unroll") for (int k = 0; k < 2; ++k) dst[m][k] = *(const PG8_LAS bf16x8*)(lds + PG8_SA(b, h) + aoff + m * 2048 + k * 1024); } while (0)
; #define PG8_LDB(dst, b, h) do { _Pragma("unroll") for (int n = 0; n < 2; ++n) _Pragma("unroll") for (int k = 0; k < 2; ++k) dst[n][k] = *(const PG8_LAS bf16x8*)(lds + PG8_SB(b, h) + boff + n * 2048 + k * 1024); } while (0)
; #define PG8_MMA(ai, bj, At, Bt) do { __builtin_amdgcn_s_setprio(1); _Pragma("unroll") for (int m = 0; m < 4; ++m) _Pragma("unroll") for (int n = 0; n < 2; ++n) _Pragma("unroll") for (int k = 0; k < 2; ++k) \
;         acc[ai][bj][m][n] = __builtin_amdgcn_mfma_f32_16x16x32_bf16(Bt[n][k], At[m][k], acc[ai][bj][m][n], 0, 0, 0); __builtin_amdgcn_s_setprio(0); } while (0)
; #define PG8_WAIT_V(n) asm volatile("s_waitcnt vmcnt(" #n ")" ::: "memory")
; #define PG8_WAIT_L(n) asm volatile("s_waitcnt lgkmcnt(" #n ")" ::: "memory")
; #define PG8_BAR __builtin_amdgcn_s_barrier()
; #define PG8_SCHED __builtin_amdgcn_sched_barrier(0)
; template <class Epi, class Sched, bool ALIGN_EPI = false, bool SP2 = false>
; __device__ __forceinline__ void gemm_phase(PG8_LAS unsigned char* lds, const Gemm g, const Sched& S, const Epi& E) {
;     ...
;             PG8_LDB(B0, 0, 0); PG8_LDB(B1, 0, 1); PG8_SCHED; PG8_LDA(At, 0, 0); PG8_STAGE(PG8_SA(1, 1), a1 + hstep, voffA);
;             PG8_WAIT_V(8); PG8_WAIT_L(0); PG8_BAR; PG8_MMA(0, 0, At, B0); PG8_MMA(0, 1, At, B1); PG8_BAR; PG8_SCHED;
;             PG8_LDA(At, 0, 1); PG8_STAGE(PG8_SB(0, 0), b2, voffB); PG8_STAGE(PG8_SB(0, 1), b2 + hstep, voffB); PG8_STAGE(PG8_SA(0, 0), a2, voffA);
;             PG8_WAIT_V(8); PG8_WAIT_L(0); PG8_BAR; PG8_MMA(1, 0, At, B0); PG8_MMA(1, 1, At, B1); PG8_BAR; PG8_SCHED;
.LBB0_810:
	ds_read_b128 v[154:157], v150
	ds_read_b128 v[158:161], v150 offset:1024
	ds_read_b128 v[162:165], v150 offset:2048
	ds_read_b128 v[166:169], v150 offset:3072
	ds_read_b128 v[170:173], v151
	ds_read_b128 v[174:177], v151 offset:1024
	ds_read_b128 v[178:181], v151 offset:2048
	ds_read_b128 v[182:185], v151 offset:3072
	s_add_u32 s38, s20, 0xfffc0080
	s_addc_u32 s39, s21, -1
	s_cmp_eq_u32 s69, 12
	s_cselect_b32 s45, s15, s39
	s_cselect_b32 s44, s65, s38
	s_cselect_b32 s39, s13, s68
	s_cselect_b32 s38, s66, s67
	s_add_i32 m0, s35, 0xc000
	ds_read_b128 v[186:189], v152
	ds_read_b128 v[190:193], v152 offset:1024
	ds_read_b128 v[198:201], v152 offset:2048
	ds_read_b128 v[202:205], v152 offset:3072
	ds_read_b128 v[206:209], v152 offset:4096
	ds_read_b128 v[210:213], v152 offset:5120
	ds_read_b128 v[214:217], v152 offset:6144
	ds_read_b128 v[218:221], v152 offset:7168
	global_load_lds_dwordx4 v136, s[20:21]
	s_add_i32 m0, s35, 0xe000
	s_nop 0
	global_load_lds_dwordx4 v138, s[20:21]
	s_waitcnt vmcnt(8)
	s_waitcnt lgkmcnt(0)
	s_barrier
	v_mfma_f32_16x16x32_bf16 v[124:127], v[154:157], v[186:189], v[124:127]
	v_mfma_f32_16x16x32_bf16 v[116:119], v[162:165], v[186:189], v[116:119]
	v_mfma_f32_16x16x32_bf16 v[108:111], v[154:157], v[198:201], v[108:111]
	v_mfma_f32_16x16x32_bf16 v[100:103], v[162:165], v[198:201], v[100:103]
	v_mfma_f32_16x16x32_bf16 v[92:95], v[154:157], v[206:209], v[92:95]
	v_mfma_f32_16x16x32_bf16 v[84:87], v[162:165], v[206:209], v[84:87]
	v_mfma_f32_16x16x32_bf16 v[76:79], v[154:157], v[214:217], v[76:79]
	v_mfma_f32_16x16x32_bf16 v[68:71], v[162:165], v[214:217], v[68:71]
	v_mfma_f32_16x16x32_bf16 v[124:127], v[158:161], v[190:193], v[124:127]
	v_mfma_f32_16x16x32_bf16 v[116:119], v[166:169], v[190:193], v[116:119]
	v_mfma_f32_16x16x32_bf16 v[108:111], v[158:161], v[202:205], v[108:111]
	v_mfma_f32_16x16x32_bf16 v[100:103], v[166:169], v[202:205], v[100:103]
	v_mfma_f32_16x16x32_bf16 v[92:95], v[158:161], v[210:213], v[92:95]
	v_mfma_f32_16x16x32_bf16 v[84:87], v[166:169], v[210:213], v[84:87]
	v_mfma_f32_16x16x32_bf16 v[76:79], v[158:161], v[218:221], v[76:79]
	v_mfma_f32_16x16x32_bf16 v[68:71], v[166:169], v[218:221], v[68:71]
	v_mfma_f32_16x16x32_bf16 v[120:123], v[170:173], v[186:189], v[120:123]
	v_mfma_f32_16x16x32_bf16 v[112:115], v[178:181], v[186:189], v[112:115]
	v_mfma_f32_16x16x32_bf16 v[104:107], v[170:173], v[198:201], v[104:107]
	v_mfma_f32_16x16x32_bf16 v[96:99], v[178:181], v[198:201], v[96:99]
	v_mfma_f32_16x16x32_bf16 v[88:91], v[170:173], v[206:209], v[88:91]
	v_mfma_f32_16x16x32_bf16 v[80:83], v[178:181], v[206:209], v[80:83]
	v_mfma_f32_16x16x32_bf16 v[72:75], v[170:173], v[214:217], v[72:75]
	v_mfma_f32_16x16x32_bf16 v[64:67], v[178:181], v[214:217], v[64:67]
	v_mfma_f32_16x16x32_bf16 v[120:123], v[174:177], v[190:193], v[120:123]
	v_mfma_f32_16x16x32_bf16 v[112:115], v[182:185], v[190:193], v[112:115]
	v_mfma_f32_16x16x32_bf16 v[104:107], v[174:177], v[202:205], v[104:107]
	v_mfma_f32_16x16x32_bf16 v[96:99], v[182:185], v[202:205], v[96:99]
	v_mfma_f32_16x16x32_bf16 v[88:91], v[174:177], v[210:213], v[88:91]
	v_mfma_f32_16x16x32_bf16 v[80:83], v[182:185], v[210:213], v[80:83]
	v_mfma_f32_16x16x32_bf16 v[72:75], v[174:177], v[218:221], v[72:75]
	v_mfma_f32_16x16x32_bf16 v[64:67], v[182:185], v[218:221], v[64:67]
	s_barrier
	s_add_i32 s70, s60, s52
	s_add_u32 s98, s38, s8
	s_addc_u32 s99, s39, s9
	s_add_u32 s100, s44, s8
	s_addc_u32 s101, s45, s9
	s_mov_b32 m0, s70
	ds_read_b128 v[186:189], v152 offset:16384
	ds_read_b128 v[190:193], v152 offset:17408
	ds_read_b128 v[198:201], v152 offset:18432
	ds_read_b128 v[202:205], v152 offset:19456
	ds_read_b128 v[206:209], v152 offset:20480
	ds_read_b128 v[210:213], v152 offset:21504
	ds_read_b128 v[214:217], v152 offset:22528
	ds_read_b128 v[218:221], v152 offset:23552
	global_load_lds_dwordx4 v132, s[38:39]
	s_add_i32 m0, s70, 0x2000
	s_add_u32 s70, s38, 0x40000
	s_addc_u32 s71, s39, 0
	s_add_i32 s72, s61, s52
	global_load_lds_dwordx4 v128, s[38:39]
	s_mov_b32 m0, s72
	s_nop 0
	global_load_lds_dwordx4 v132, s[70:71]
	s_add_i32 m0, s72, 0x2000
	s_nop 0
	global_load_lds_dwordx4 v128, s[70:71]
	s_mov_b32 m0, s35
	s_nop 0
	global_load_lds_dwordx4 v134, s[44:45]
	s_mov_b32 m0, s54
	s_nop 0
	global_load_lds_dwordx4 v130, s[44:45]
	s_waitcnt vmcnt(8)
	s_waitcnt lgkmcnt(0)
	s_barrier
	v_mfma_f32_16x16x32_bf16 v[60:63], v[154:157], v[186:189], v[60:63]
	v_mfma_f32_16x16x32_bf16 v[52:55], v[162:165], v[186:189], v[52:55]
	v_mfma_f32_16x16x32_bf16 v[44:47], v[154:157], v[198:201], v[44:47]
	v_mfma_f32_16x16x32_bf16 v[36:39], v[162:165], v[198:201], v[36:39]
	v_mfma_f32_16x16x32_bf16 v[28:31], v[154:157], v[206:209], v[28:31]
	v_mfma_f32_16x16x32_bf16 v[20:23], v[162:165], v[206:209], v[20:23]
	v_mfma_f32_16x16x32_bf16 v[12:15], v[154:157], v[214:217], v[12:15]
	v_mfma_f32_16x16x32_bf16 v[4:7], v[162:165], v[214:217], v[4:7]
	v_mfma_f32_16x16x32_bf16 v[60:63], v[158:161], v[190:193], v[60:63]
	v_mfma_f32_16x16x32_bf16 v[52:55], v[166:169], v[190:193], v[52:55]
	v_mfma_f32_16x16x32_bf16 v[44:47], v[158:161], v[202:205], v[44:47]
	v_mfma_f32_16x16x32_bf16 v[36:39], v[166:169], v[202:205], v[36:39]
	v_mfma_f32_16x16x32_bf16 v[28:31], v[158:161], v[210:213], v[28:31]
	v_mfma_f32_16x16x32_bf16 v[20:23], v[166:169], v[210:213], v[20:23]
	v_mfma_f32_16x16x32_bf16 v[12:15], v[158:161], v[218:221], v[12:15]
	v_mfma_f32_16x16x32_bf16 v[4:7], v[166:169], v[218:221], v[4:7]
	v_mfma_f32_16x16x32_bf16 v[56:59], v[170:173], v[186:189], v[56:59]
	v_mfma_f32_16x16x32_bf16 v[48:51], v[178:181], v[186:189], v[48:51]
	v_mfma_f32_16x16x32_bf16 v[40:43], v[170:173], v[198:201], v[40:43]
	v_mfma_f32_16x16x32_bf16 v[32:35], v[178:181], v[198:201], v[32:35]
	v_mfma_f32_16x16x32_bf16 v[24:27], v[170:173], v[206:209], v[24:27]
	v_mfma_f32_16x16x32_bf16 v[16:19], v[178:181], v[206:209], v[16:19]
	v_mfma_f32_16x16x32_bf16 v[8:11], v[170:173], v[214:217], v[8:11]
	v_mfma_f32_16x16x32_bf16 v[0:3], v[178:181], v[214:217], v[0:3]
	v_mfma_f32_16x16x32_bf16 v[56:59], v[174:177], v[190:193], v[56:59]
	v_mfma_f32_16x16x32_bf16 v[48:51], v[182:185], v[190:193], v[48:51]
	v_mfma_f32_16x16x32_bf16 v[40:43], v[174:177], v[202:205], v[40:43]
	v_mfma_f32_16x16x32_bf16 v[32:35], v[182:185], v[202:205], v[32:35]
	v_mfma_f32_16x16x32_bf16 v[24:27], v[174:177], v[210:213], v[24:27]
	v_mfma_f32_16x16x32_bf16 v[16:19], v[182:185], v[210:213], v[16:19]
	v_mfma_f32_16x16x32_bf16 v[8:11], v[174:177], v[218:221], v[8:11]
	v_mfma_f32_16x16x32_bf16 v[0:3], v[182:185], v[218:221], v[0:3]
	s_barrier
; #define PG8_STAGE(bufoff, gbase, voff) do { _Pragma("unroll") for (int _i = 0; _i < 2; ++_i) \
;         __builtin_amdgcn_global_load_lds((const unsigned*)((const char*)(gbase) + (voff)[_i]), (PG8_LAS unsigned*)(lds + (bufoff) + ldsw + _i * 8192), 16, 0, 0); } while (0)
; #define PG8_LDA(dst, b, h) do { _Pragma("unroll") for (int m = 0; m < 4; ++m) _Pragma("unroll") for (int k = 0; k < 2; ++k) dst[m][k] = *(const PG8_LAS bf16x8*)(lds + PG8_SA(b, h) + aoff + m * 2048 + k * 1024); } while (0)
; #define PG8_LDB(dst, b, h) do { _Pragma("unroll") for (int n = 0; n < 2; ++n) _Pragma("unroll") for (int k = 0; k < 2; ++k) dst[n][k] = *(const PG8_LAS bf16x8*)(lds + PG8_SB(b, h) + boff + n * 2048 + k * 1024); } while (0)
; #define PG8_MMA(ai, bj, At, Bt) do { __builtin_amdgcn_s_setprio(1); _Pragma("unroll") for (int m = 0; m < 4; ++m) _Pragma("unroll") for (int n = 0; n < 2; ++n) _Pragma("unroll") for (int k = 0; k < 2; ++k) \
;         acc[ai][bj][m][n] = __builtin_amdgcn_mfma_f32_16x16x32_bf16(Bt[n][k], At[m][k], acc[ai][bj][m][n], 0, 0, 0); __builtin_amdgcn_s_setprio(0); } while (0)
; #define PG8_WAIT_V(n) asm volatile("s_waitcnt vmcnt(" #n ")" ::: "memory")
; #define PG8_WAIT_L(n) asm volatile("s_waitcnt lgkmcnt(" #n ")" ::: "memory")
; #define PG8_BAR __builtin_amdgcn_s_barrier()
; #define PG8_SCHED __builtin_amdgcn_sched_barrier(0)
; template <class Epi, class Sched, bool ALIGN_EPI = false, bool SP2 = false>
; __device__ __forceinline__ void gemm_phase(PG8_LAS unsigned char* lds, const Gemm g, const Sched& S, const Epi& E) {
;     ...
;         for (int t = 0; t < nt; t += 2) {
;     ...
;             PG8_LDB(B0, 1, 0); PG8_LDB(B1, 1, 1); PG8_SCHED; PG8_LDA(At, 1, 0); PG8_STAGE(PG8_SA(0, 1), a2 + hstep, voffA);
;             PG8_WAIT_V(8); PG8_WAIT_L(0); PG8_BAR; PG8_MMA(0, 0, At, B0); PG8_MMA(0, 1, At, B1); PG8_BAR; PG8_SCHED;
;             PG8_LDA(At, 1, 1); PG8_STAGE(PG8_SB(1, 0), b3, voffB); PG8_STAGE(PG8_SB(1, 1), b3 + hstep, voffB); PG8_STAGE(PG8_SA(1, 0), a3, voffA);
;             PG8_WAIT_V(8); PG8_WAIT_L(0); PG8_BAR; PG8_MMA(1, 0, At, B0); PG8_MMA(1, 1, At, B1); PG8_BAR; PG8_SCHED;
	s_add_i32 s70, 0, 0x18000
	v_add_u32_e32 v153, s70, v147
	s_add_i32 s71, 0, 0x1c000
	ds_read_b128 v[154:157], v153
	ds_read_b128 v[158:161], v153 offset:1024
	ds_read_b128 v[162:165], v153 offset:2048
	ds_read_b128 v[166:169], v153 offset:3072
	v_add_u32_e32 v153, s71, v147
	ds_read_b128 v[170:173], v153
	ds_read_b128 v[174:177], v153 offset:1024
	ds_read_b128 v[178:181], v153 offset:2048
	ds_read_b128 v[182:185], v153 offset:3072
	s_add_u32 s44, s44, 0x40000
	s_addc_u32 s45, s45, 0
	s_mov_b32 m0, s55
	ds_read_b128 v[186:189], v152 offset:32768
	ds_read_b128 v[190:193], v152 offset:33792
	ds_read_b128 v[198:201], v152 offset:34816
	ds_read_b128 v[202:205], v152 offset:35840
	ds_read_b128 v[206:209], v152 offset:36864
	ds_read_b128 v[210:213], v152 offset:37888
	ds_read_b128 v[214:217], v152 offset:38912
	ds_read_b128 v[218:221], v152 offset:39936
	global_load_lds_dwordx4 v134, s[44:45]
	s_mov_b32 m0, s56
	s_nop 0
	global_load_lds_dwordx4 v130, s[44:45]
	s_waitcnt vmcnt(8)
	s_waitcnt lgkmcnt(0)
	s_barrier
	v_mfma_f32_16x16x32_bf16 v[124:127], v[154:157], v[186:189], v[124:127]
	v_mfma_f32_16x16x32_bf16 v[116:119], v[162:165], v[186:189], v[116:119]
	v_mfma_f32_16x16x32_bf16 v[108:111], v[154:157], v[198:201], v[108:111]
	v_mfma_f32_16x16x32_bf16 v[100:103], v[162:165], v[198:201], v[100:103]
	v_mfma_f32_16x16x32_bf16 v[92:95], v[154:157], v[206:209], v[92:95]
	v_mfma_f32_16x16x32_bf16 v[84:87], v[162:165], v[206:209], v[84:87]
	v_mfma_f32_16x16x32_bf16 v[76:79], v[154:157], v[214:217], v[76:79]
	v_mfma_f32_16x16x32_bf16 v[68:71], v[162:165], v[214:217], v[68:71]
	v_mfma_f32_16x16x32_bf16 v[124:127], v[158:161], v[190:193], v[124:127]
	v_mfma_f32_16x16x32_bf16 v[116:119], v[166:169], v[190:193], v[116:119]
	v_mfma_f32_16x16x32_bf16 v[108:111], v[158:161], v[202:205], v[108:111]
	v_mfma_f32_16x16x32_bf16 v[100:103], v[166:169], v[202:205], v[100:103]
	v_mfma_f32_16x16x32_bf16 v[92:95], v[158:161], v[210:213], v[92:95]
	v_mfma_f32_16x16x32_bf16 v[84:87], v[166:169], v[210:213], v[84:87]
	v_mfma_f32_16x16x32_bf16 v[76:79], v[158:161], v[218:221], v[76:79]
	v_mfma_f32_16x16x32_bf16 v[68:71], v[166:169], v[218:221], v[68:71]
	v_mfma_f32_16x16x32_bf16 v[120:123], v[170:173], v[186:189], v[120:123]
	v_mfma_f32_16x16x32_bf16 v[112:115], v[178:181], v[186:189], v[112:115]
	v_mfma_f32_16x16x32_bf16 v[104:107], v[170:173], v[198:201], v[104:107]
	v_mfma_f32_16x16x32_bf16 v[96:99], v[178:181], v[198:201], v[96:99]
	v_mfma_f32_16x16x32_bf16 v[88:91], v[170:173], v[206:209], v[88:91]
	v_mfma_f32_16x16x32_bf16 v[80:83], v[178:181], v[206:209], v[80:83]
	v_mfma_f32_16x16x32_bf16 v[72:75], v[170:173], v[214:217], v[72:75]
	v_mfma_f32_16x16x32_bf16 v[64:67], v[178:181], v[214:217], v[64:67]
	v_mfma_f32_16x16x32_bf16 v[120:123], v[174:177], v[190:193], v[120:123]
	v_mfma_f32_16x16x32_bf16 v[112:115], v[182:185], v[190:193], v[112:115]
	v_mfma_f32_16x16x32_bf16 v[104:107], v[174:177], v[202:205], v[104:107]
	v_mfma_f32_16x16x32_bf16 v[96:99], v[182:185], v[202:205], v[96:99]
	v_mfma_f32_16x16x32_bf16 v[88:91], v[174:177], v[210:213], v[88:91]
	v_mfma_f32_16x16x32_bf16 v[80:83], v[182:185], v[210:213], v[80:83]
	v_mfma_f32_16x16x32_bf16 v[72:75], v[174:177], v[218:221], v[72:75]
	v_mfma_f32_16x16x32_bf16 v[64:67], v[182:185], v[218:221], v[64:67]
	s_barrier
	s_add_i32 s44, s70, s52
	s_mov_b32 m0, s44
	ds_read_b128 v[186:189], v152 offset:49152
	ds_read_b128 v[190:193], v152 offset:50176
	ds_read_b128 v[198:201], v152 offset:51200
	ds_read_b128 v[202:205], v152 offset:52224
	ds_read_b128 v[206:209], v152 offset:53248
	ds_read_b128 v[210:213], v152 offset:54272
	ds_read_b128 v[214:217], v152 offset:55296
	ds_read_b128 v[218:221], v152 offset:56320
	global_load_lds_dwordx4 v132, s[98:99]
	s_add_i32 m0, s44, 0x2000
	s_add_u32 s38, s38, 0x40080
	s_addc_u32 s39, s39, 0
	s_add_i32 s44, s71, s52
	global_load_lds_dwordx4 v128, s[98:99]
	s_mov_b32 m0, s44
	s_nop 0
	global_load_lds_dwordx4 v132, s[38:39]
	s_add_i32 m0, s44, 0x2000
	s_nop 0
	global_load_lds_dwordx4 v128, s[38:39]
	s_mov_b32 m0, s58
	s_nop 0
	global_load_lds_dwordx4 v134, s[100:101]
	s_mov_b32 m0, s59
	s_nop 0
	global_load_lds_dwordx4 v130, s[100:101]
	s_waitcnt vmcnt(8)
	s_waitcnt lgkmcnt(0)
	s_barrier
	v_mfma_f32_16x16x32_bf16 v[60:63], v[154:157], v[186:189], v[60:63]
	v_mfma_f32_16x16x32_bf16 v[52:55], v[162:165], v[186:189], v[52:55]
	v_mfma_f32_16x16x32_bf16 v[44:47], v[154:157], v[198:201], v[44:47]
	v_mfma_f32_16x16x32_bf16 v[36:39], v[162:165], v[198:201], v[36:39]
	v_mfma_f32_16x16x32_bf16 v[28:31], v[154:157], v[206:209], v[28:31]
	v_mfma_f32_16x16x32_bf16 v[20:23], v[162:165], v[206:209], v[20:23]
	v_mfma_f32_16x16x32_bf16 v[12:15], v[154:157], v[214:217], v[12:15]
	v_mfma_f32_16x16x32_bf16 v[4:7], v[162:165], v[214:217], v[4:7]
	v_mfma_f32_16x16x32_bf16 v[60:63], v[158:161], v[190:193], v[60:63]
	v_mfma_f32_16x16x32_bf16 v[52:55], v[166:169], v[190:193], v[52:55]
	v_mfma_f32_16x16x32_bf16 v[44:47], v[158:161], v[202:205], v[44:47]
	v_mfma_f32_16x16x32_bf16 v[36:39], v[166:169], v[202:205], v[36:39]
	v_mfma_f32_16x16x32_bf16 v[28:31], v[158:161], v[210:213], v[28:31]
	v_mfma_f32_16x16x32_bf16 v[20:23], v[166:169], v[210:213], v[20:23]
	v_mfma_f32_16x16x32_bf16 v[12:15], v[158:161], v[218:221], v[12:15]
	v_mfma_f32_16x16x32_bf16 v[4:7], v[166:169], v[218:221], v[4:7]
	v_mfma_f32_16x16x32_bf16 v[56:59], v[170:173], v[186:189], v[56:59]
	v_mfma_f32_16x16x32_bf16 v[48:51], v[178:181], v[186:189], v[48:51]
	v_mfma_f32_16x16x32_bf16 v[40:43], v[170:173], v[198:201], v[40:43]
	v_mfma_f32_16x16x32_bf16 v[32:35], v[178:181], v[198:201], v[32:35]
	v_mfma_f32_16x16x32_bf16 v[24:27], v[170:173], v[206:209], v[24:27]
	v_mfma_f32_16x16x32_bf16 v[16:19], v[178:181], v[206:209], v[16:19]
	v_mfma_f32_16x16x32_bf16 v[8:11], v[170:173], v[214:217], v[8:11]
	v_mfma_f32_16x16x32_bf16 v[0:3], v[178:181], v[214:217], v[0:3]
	v_mfma_f32_16x16x32_bf16 v[56:59], v[174:177], v[190:193], v[56:59]
	v_mfma_f32_16x16x32_bf16 v[48:51], v[182:185], v[190:193], v[48:51]
	v_mfma_f32_16x16x32_bf16 v[40:43], v[174:177], v[202:205], v[40:43]
	v_mfma_f32_16x16x32_bf16 v[32:35], v[182:185], v[202:205], v[32:35]
	v_mfma_f32_16x16x32_bf16 v[24:27], v[174:177], v[210:213], v[24:27]
	v_mfma_f32_16x16x32_bf16 v[16:19], v[182:185], v[210:213], v[16:19]
	v_mfma_f32_16x16x32_bf16 v[8:11], v[174:177], v[218:221], v[8:11]
	v_mfma_f32_16x16x32_bf16 v[0:3], v[182:185], v[218:221], v[0:3]
	s_barrier
	s_add_i32 s69, s69, 2
	s_add_u32 s20, s20, 0x100
	s_addc_u32 s21, s21, 0
	s_add_u32 s67, s67, 0x100
	s_addc_u32 s68, s68, 0
	s_cmp_gt_u32 s69, 13
	s_cbranch_scc0 .LBB0_810
	v_readlane_b32 s101, v249, 49
	s_nop 3
	s_cmp_eq_u32 s101, 0
	s_cbranch_scc1 .Ldw_done_1
	v_readlane_b32 s100, v249, 18
	s_nop 3
	s_cmp_lg_u32 s100, 0
	s_cbranch_scc1 .Ldw_ok_1
	s_add_u32 s98, s28, 0x183500
	s_addc_u32 s99, s29, 0
	v_mov_b32_e32 v251, 0
	s_mov_b32 s100, 0

; #define PG8_STAGE(bufoff, gbase, voff) do { _Pragma("unroll") for (int _i = 0; _i < 2; ++_i) \
;         __builtin_amdgcn_global_load_lds((const unsigned*)((const char*)(gbase) + (voff)[_i]), (PG8_LAS unsigned*)(lds + (bufoff) + ldsw + _i * 8192), 16, 0, 0); } while (0)
; #define PG8_LDA(dst, b, h) do { _Pragma("unroll") for (int m = 0; m < 4; ++m) _Pragma("unroll") for (int k = 0; k < 2; ++k) dst[m][k] = *(const PG8_LAS bf16x8*)(lds + PG8_SA(b, h) + aoff + m * 2048 + k * 1024); } while (0)
; #define PG8_LDB(dst, b, h) do { _Pragma("unroll") for (int n = 0; n < 2; ++n) _Pragma("unroll") for (int k = 0; k < 2; ++k) dst[n][k] = *(const PG8_LAS bf16x8*)(lds + PG8_SB(b, h) + boff + n * 2048 + k * 1024); } while (0)
; #define PG8_MMA(ai, bj, At, Bt) do { __builtin_amdgcn_s_setprio(1); _Pragma("unroll") for (int m = 0; m < 4; ++m) _Pragma("unroll") for (int n = 0; n < 2; ++n) _Pragma("unroll") for (int k = 0; k < 2; ++k) \
;         acc[ai][bj][m][n] = __builtin_amdgcn_mfma_f32_16x16x32_bf16(Bt[n][k], At[m][k], acc[ai][bj][m][n], 0, 0, 0); __builtin_amdgcn_s_setprio(0); } while (0)
; #define PG8_WAIT_V(n) asm volatile("s_waitcnt vmcnt(" #n ")" ::: "memory")
; #define PG8_WAIT_L(n) asm volatile("s_waitcnt lgkmcnt(" #n ")" ::: "memory")
; #define PG8_BAR __builtin_amdgcn_s_barrier()
; #define PG8_SCHED __builtin_amdgcn_sched_barrier(0)
; template <class Epi, class Sched, bool ALIGN_EPI = false, bool SP2 = false>
; __device__ __forceinline__ void gemm_phase(PG8_LAS unsigned char* lds, const Gemm g, const Sched& S, const Epi& E) {
;     ...
;             PG8_LDB(B0, 0, 0); PG8_LDB(B1, 0, 1); PG8_SCHED; PG8_LDA(At, 0, 0); PG8_STAGE(PG8_SA(1, 1), a1 + hstep, voffA);
;             PG8_WAIT_V(8); PG8_WAIT_L(0); PG8_BAR; PG8_MMA(0, 0, At, B0); PG8_MMA(0, 1, At, B1); PG8_BAR; PG8_SCHED;
;             PG8_LDA(At, 0, 1); PG8_STAGE(PG8_SB(0, 0), b2, voffB); PG8_STAGE(PG8_SB(0, 1), b2 + hstep, voffB); PG8_STAGE(PG8_SA(0, 0), a2, voffA);
;             PG8_WAIT_V(8); PG8_WAIT_L(0); PG8_BAR; PG8_MMA(1, 0, At, B0); PG8_MMA(1, 1, At, B1); PG8_BAR; PG8_SCHED;
.LBB0_1200:
	ds_read_b128 v[140:143], v163
	ds_read_b128 v[168:171], v163 offset:1024
	ds_read_b128 v[172:175], v163 offset:2048
	ds_read_b128 v[176:179], v163 offset:3072
	ds_read_b128 v[180:183], v164
	ds_read_b128 v[184:187], v164 offset:1024
	ds_read_b128 v[188:191], v164 offset:2048
	ds_read_b128 v[192:195], v164 offset:3072
	s_add_u32 s34, s20, 0xfffc0080
	s_addc_u32 s35, s21, -1
	s_cmp_eq_u32 s88, 12
	s_cselect_b32 s63, s1, s35
	s_cselect_b32 s62, s57, s34
	s_cselect_b32 s35, s55, s87
	s_cselect_b32 s34, s85, s86
	s_add_i32 m0, s71, 0xc000
	ds_read_b128 v[198:201], v165
	ds_read_b128 v[202:205], v165 offset:1024
	ds_read_b128 v[206:209], v165 offset:2048
	ds_read_b128 v[210:213], v165 offset:3072
	ds_read_b128 v[214:217], v165 offset:4096
	ds_read_b128 v[218:221], v165 offset:5120
	ds_read_b128 v[222:225], v165 offset:6144
	ds_read_b128 v[226:229], v165 offset:7168
	global_load_lds_dwordx4 v132, s[20:21]
	s_add_i32 m0, s71, 0xe000
	s_nop 0
	global_load_lds_dwordx4 v134, s[20:21]
	s_waitcnt vmcnt(8)
	s_waitcnt lgkmcnt(0)
	s_barrier
	v_mfma_f32_16x16x32_bf16 v[124:127], v[140:143], v[198:201], v[124:127]
	v_mfma_f32_16x16x32_bf16 v[120:123], v[172:175], v[198:201], v[120:123]
	v_mfma_f32_16x16x32_bf16 v[108:111], v[140:143], v[206:209], v[108:111]
	v_mfma_f32_16x16x32_bf16 v[104:107], v[172:175], v[206:209], v[104:107]
	v_mfma_f32_16x16x32_bf16 v[92:95], v[140:143], v[214:217], v[92:95]
	v_mfma_f32_16x16x32_bf16 v[88:91], v[172:175], v[214:217], v[88:91]
	v_mfma_f32_16x16x32_bf16 v[76:79], v[140:143], v[222:225], v[76:79]
	v_mfma_f32_16x16x32_bf16 v[72:75], v[172:175], v[222:225], v[72:75]
	v_mfma_f32_16x16x32_bf16 v[124:127], v[168:171], v[202:205], v[124:127]
	v_mfma_f32_16x16x32_bf16 v[120:123], v[176:179], v[202:205], v[120:123]
	v_mfma_f32_16x16x32_bf16 v[108:111], v[168:171], v[210:213], v[108:111]
	v_mfma_f32_16x16x32_bf16 v[104:107], v[176:179], v[210:213], v[104:107]
	v_mfma_f32_16x16x32_bf16 v[92:95], v[168:171], v[218:221], v[92:95]
	v_mfma_f32_16x16x32_bf16 v[88:91], v[176:179], v[218:221], v[88:91]
	v_mfma_f32_16x16x32_bf16 v[76:79], v[168:171], v[226:229], v[76:79]
	v_mfma_f32_16x16x32_bf16 v[72:75], v[176:179], v[226:229], v[72:75]
	v_mfma_f32_16x16x32_bf16 v[116:119], v[180:183], v[198:201], v[116:119]
	v_mfma_f32_16x16x32_bf16 v[112:115], v[188:191], v[198:201], v[112:115]
	v_mfma_f32_16x16x32_bf16 v[100:103], v[180:183], v[206:209], v[100:103]
	v_mfma_f32_16x16x32_bf16 v[96:99], v[188:191], v[206:209], v[96:99]
	v_mfma_f32_16x16x32_bf16 v[84:87], v[180:183], v[214:217], v[84:87]
	v_mfma_f32_16x16x32_bf16 v[80:83], v[188:191], v[214:217], v[80:83]
	v_mfma_f32_16x16x32_bf16 v[68:71], v[180:183], v[222:225], v[68:71]
	v_mfma_f32_16x16x32_bf16 v[64:67], v[188:191], v[222:225], v[64:67]
	v_mfma_f32_16x16x32_bf16 v[116:119], v[184:187], v[202:205], v[116:119]
	v_mfma_f32_16x16x32_bf16 v[112:115], v[192:195], v[202:205], v[112:115]
	v_mfma_f32_16x16x32_bf16 v[100:103], v[184:187], v[210:213], v[100:103]
	v_mfma_f32_16x16x32_bf16 v[96:99], v[192:195], v[210:213], v[96:99]
	v_mfma_f32_16x16x32_bf16 v[84:87], v[184:187], v[218:221], v[84:87]
	v_mfma_f32_16x16x32_bf16 v[80:83], v[192:195], v[218:221], v[80:83]
	v_mfma_f32_16x16x32_bf16 v[68:71], v[184:187], v[226:229], v[68:71]
	v_mfma_f32_16x16x32_bf16 v[64:67], v[192:195], v[226:229], v[64:67]
	s_barrier
	s_add_i32 s89, s77, s70
	s_add_u32 s98, s34, s18
	s_addc_u32 s99, s35, s19
	s_add_u32 s100, s62, s18
	s_addc_u32 s101, s63, s19
	s_mov_b32 m0, s89
	ds_read_b128 v[198:201], v165 offset:16384
	ds_read_b128 v[202:205], v165 offset:17408
	ds_read_b128 v[206:209], v165 offset:18432
	ds_read_b128 v[210:213], v165 offset:19456
	ds_read_b128 v[214:217], v165 offset:20480
	ds_read_b128 v[218:221], v165 offset:21504
	ds_read_b128 v[222:225], v165 offset:22528
	ds_read_b128 v[226:229], v165 offset:23552
	global_load_lds_dwordx4 v146, s[34:35]
	s_add_i32 m0, s89, 0x2000
	s_add_u32 s90, s34, 0x40000
	s_addc_u32 s91, s35, 0
	s_add_i32 s89, s78, s70
	global_load_lds_dwordx4 v150, s[34:35]
	s_mov_b32 m0, s89
	s_nop 0
	global_load_lds_dwordx4 v146, s[90:91]
	s_add_i32 m0, s89, 0x2000
	s_nop 0
	global_load_lds_dwordx4 v150, s[90:91]
	s_mov_b32 m0, s71
	s_nop 0
	global_load_lds_dwordx4 v144, s[62:63]
	s_mov_b32 m0, s72
	s_nop 0
	global_load_lds_dwordx4 v148, s[62:63]
	s_waitcnt vmcnt(8)
	s_waitcnt lgkmcnt(0)
	s_barrier
	v_mfma_f32_16x16x32_bf16 v[60:63], v[140:143], v[198:201], v[60:63]
	v_mfma_f32_16x16x32_bf16 v[56:59], v[172:175], v[198:201], v[56:59]
	v_mfma_f32_16x16x32_bf16 v[48:51], v[140:143], v[206:209], v[48:51]
	v_mfma_f32_16x16x32_bf16 v[40:43], v[172:175], v[206:209], v[40:43]
	v_mfma_f32_16x16x32_bf16 v[32:35], v[140:143], v[214:217], v[32:35]
	v_mfma_f32_16x16x32_bf16 v[24:27], v[172:175], v[214:217], v[24:27]
	v_mfma_f32_16x16x32_bf16 v[16:19], v[140:143], v[222:225], v[16:19]
	v_mfma_f32_16x16x32_bf16 v[8:11], v[172:175], v[222:225], v[8:11]
	v_mfma_f32_16x16x32_bf16 v[60:63], v[168:171], v[202:205], v[60:63]
	v_mfma_f32_16x16x32_bf16 v[56:59], v[176:179], v[202:205], v[56:59]
	v_mfma_f32_16x16x32_bf16 v[48:51], v[168:171], v[210:213], v[48:51]
	v_mfma_f32_16x16x32_bf16 v[40:43], v[176:179], v[210:213], v[40:43]
	v_mfma_f32_16x16x32_bf16 v[32:35], v[168:171], v[218:221], v[32:35]
	v_mfma_f32_16x16x32_bf16 v[24:27], v[176:179], v[218:221], v[24:27]
	v_mfma_f32_16x16x32_bf16 v[16:19], v[168:171], v[226:229], v[16:19]
	v_mfma_f32_16x16x32_bf16 v[8:11], v[176:179], v[226:229], v[8:11]
	v_mfma_f32_16x16x32_bf16 v[52:55], v[180:183], v[198:201], v[52:55]
	v_mfma_f32_16x16x32_bf16 v[44:47], v[188:191], v[198:201], v[44:47]
	v_mfma_f32_16x16x32_bf16 v[36:39], v[180:183], v[206:209], v[36:39]
	v_mfma_f32_16x16x32_bf16 v[28:31], v[188:191], v[206:209], v[28:31]
	v_mfma_f32_16x16x32_bf16 v[20:23], v[180:183], v[214:217], v[20:23]
	v_mfma_f32_16x16x32_bf16 v[12:15], v[188:191], v[214:217], v[12:15]
	v_mfma_f32_16x16x32_bf16 v[4:7], v[180:183], v[222:225], v[4:7]
	v_mfma_f32_16x16x32_bf16 v[0:3], v[188:191], v[222:225], v[0:3]
	v_mfma_f32_16x16x32_bf16 v[52:55], v[184:187], v[202:205], v[52:55]
	v_mfma_f32_16x16x32_bf16 v[44:47], v[192:195], v[202:205], v[44:47]
	v_mfma_f32_16x16x32_bf16 v[36:39], v[184:187], v[210:213], v[36:39]
	v_mfma_f32_16x16x32_bf16 v[28:31], v[192:195], v[210:213], v[28:31]
	v_mfma_f32_16x16x32_bf16 v[20:23], v[184:187], v[218:221], v[20:23]
	v_mfma_f32_16x16x32_bf16 v[12:15], v[192:195], v[218:221], v[12:15]
	v_mfma_f32_16x16x32_bf16 v[4:7], v[184:187], v[226:229], v[4:7]
	v_mfma_f32_16x16x32_bf16 v[0:3], v[192:195], v[226:229], v[0:3]
	s_barrier
; #define PG8_STAGE(bufoff, gbase, voff) do { _Pragma("unroll") for (int _i = 0; _i < 2; ++_i) \
;         __builtin_amdgcn_global_load_lds((const unsigned*)((const char*)(gbase) + (voff)[_i]), (PG8_LAS unsigned*)(lds + (bufoff) + ldsw + _i * 8192), 16, 0, 0); } while (0)
; #define PG8_LDA(dst, b, h) do { _Pragma("unroll") for (int m = 0; m < 4; ++m) _Pragma("unroll") for (int k = 0; k < 2; ++k) dst[m][k] = *(const PG8_LAS bf16x8*)(lds + PG8_SA(b, h) + aoff + m * 2048 + k * 1024); } while (0)
; #define PG8_LDB(dst, b, h) do { _Pragma("unroll") for (int n = 0; n < 2; ++n) _Pragma("unroll") for (int k = 0; k < 2; ++k) dst[n][k] = *(const PG8_LAS bf16x8*)(lds + PG8_SB(b, h) + boff + n * 2048 + k * 1024); } while (0)
; #define PG8_MMA(ai, bj, At, Bt) do { __builtin_amdgcn_s_setprio(1); _Pragma("unroll") for (int m = 0; m < 4; ++m) _Pragma("unroll") for (int n = 0; n < 2; ++n) _Pragma("unroll") for (int k = 0; k < 2; ++k) \
;         acc[ai][bj][m][n] = __builtin_amdgcn_mfma_f32_16x16x32_bf16(Bt[n][k], At[m][k], acc[ai][bj][m][n], 0, 0, 0); __builtin_amdgcn_s_setprio(0); } while (0)
; #define PG8_WAIT_V(n) asm volatile("s_waitcnt vmcnt(" #n ")" ::: "memory")
; #define PG8_WAIT_L(n) asm volatile("s_waitcnt lgkmcnt(" #n ")" ::: "memory")
; #define PG8_BAR __builtin_amdgcn_s_barrier()
; #define PG8_SCHED __builtin_amdgcn_sched_barrier(0)
; template <class Epi, class Sched, bool ALIGN_EPI = false, bool SP2 = false>
; __device__ __forceinline__ void gemm_phase(PG8_LAS unsigned char* lds, const Gemm g, const Sched& S, const Epi& E) {
;     ...
;         for (int t = 0; t < nt; t += 2) {
;     ...
;             PG8_LDB(B0, 1, 0); PG8_LDB(B1, 1, 1); PG8_SCHED; PG8_LDA(At, 1, 0); PG8_STAGE(PG8_SA(0, 1), a2 + hstep, voffA);
;             PG8_WAIT_V(8); PG8_WAIT_L(0); PG8_BAR; PG8_MMA(0, 0, At, B0); PG8_MMA(0, 1, At, B1); PG8_BAR; PG8_SCHED;
;             PG8_LDA(At, 1, 1); PG8_STAGE(PG8_SB(1, 0), b3, voffB); PG8_STAGE(PG8_SB(1, 1), b3 + hstep, voffB); PG8_STAGE(PG8_SA(1, 0), a3, voffA);
;             PG8_WAIT_V(8); PG8_WAIT_L(0); PG8_BAR; PG8_MMA(1, 0, At, B0); PG8_MMA(1, 1, At, B1); PG8_BAR; PG8_SCHED;
	s_add_i32 s89, 0, 0x18000
	v_add_u32_e32 v128, s89, v161
	s_add_i32 s90, 0, 0x1c000
	ds_read_b128 v[140:143], v128
	ds_read_b128 v[168:171], v128 offset:1024
	ds_read_b128 v[172:175], v128 offset:2048
	ds_read_b128 v[176:179], v128 offset:3072
	v_add_u32_e32 v128, s90, v161
	ds_read_b128 v[180:183], v128
	ds_read_b128 v[184:187], v128 offset:1024
	ds_read_b128 v[188:191], v128 offset:2048
	ds_read_b128 v[192:195], v128 offset:3072
	s_add_u32 s62, s62, 0x40000
	s_addc_u32 s63, s63, 0
	s_mov_b32 m0, s73
	ds_read_b128 v[198:201], v165 offset:32768
	ds_read_b128 v[202:205], v165 offset:33792
	ds_read_b128 v[206:209], v165 offset:34816
	ds_read_b128 v[210:213], v165 offset:35840
	ds_read_b128 v[214:217], v165 offset:36864
	ds_read_b128 v[218:221], v165 offset:37888
	ds_read_b128 v[222:225], v165 offset:38912
	ds_read_b128 v[226:229], v165 offset:39936
	global_load_lds_dwordx4 v144, s[62:63]
	s_mov_b32 m0, s74
	s_nop 0
	global_load_lds_dwordx4 v148, s[62:63]
	s_waitcnt vmcnt(8)
	s_waitcnt lgkmcnt(0)
	s_barrier
	v_mfma_f32_16x16x32_bf16 v[124:127], v[140:143], v[198:201], v[124:127]
	v_mfma_f32_16x16x32_bf16 v[120:123], v[172:175], v[198:201], v[120:123]
	v_mfma_f32_16x16x32_bf16 v[108:111], v[140:143], v[206:209], v[108:111]
	v_mfma_f32_16x16x32_bf16 v[104:107], v[172:175], v[206:209], v[104:107]
	v_mfma_f32_16x16x32_bf16 v[92:95], v[140:143], v[214:217], v[92:95]
	v_mfma_f32_16x16x32_bf16 v[88:91], v[172:175], v[214:217], v[88:91]
	v_mfma_f32_16x16x32_bf16 v[76:79], v[140:143], v[222:225], v[76:79]
	v_mfma_f32_16x16x32_bf16 v[72:75], v[172:175], v[222:225], v[72:75]
	v_mfma_f32_16x16x32_bf16 v[124:127], v[168:171], v[202:205], v[124:127]
	v_mfma_f32_16x16x32_bf16 v[120:123], v[176:179], v[202:205], v[120:123]
	v_mfma_f32_16x16x32_bf16 v[108:111], v[168:171], v[210:213], v[108:111]
	v_mfma_f32_16x16x32_bf16 v[104:107], v[176:179], v[210:213], v[104:107]
	v_mfma_f32_16x16x32_bf16 v[92:95], v[168:171], v[218:221], v[92:95]
	v_mfma_f32_16x16x32_bf16 v[88:91], v[176:179], v[218:221], v[88:91]
	v_mfma_f32_16x16x32_bf16 v[76:79], v[168:171], v[226:229], v[76:79]
	v_mfma_f32_16x16x32_bf16 v[72:75], v[176:179], v[226:229], v[72:75]
	v_mfma_f32_16x16x32_bf16 v[116:119], v[180:183], v[198:201], v[116:119]
	v_mfma_f32_16x16x32_bf16 v[112:115], v[188:191], v[198:201], v[112:115]
	v_mfma_f32_16x16x32_bf16 v[100:103], v[180:183], v[206:209], v[100:103]
	v_mfma_f32_16x16x32_bf16 v[96:99], v[188:191], v[206:209], v[96:99]
	v_mfma_f32_16x16x32_bf16 v[84:87], v[180:183], v[214:217], v[84:87]
	v_mfma_f32_16x16x32_bf16 v[80:83], v[188:191], v[214:217], v[80:83]
	v_mfma_f32_16x16x32_bf16 v[68:71], v[180:183], v[222:225], v[68:71]
	v_mfma_f32_16x16x32_bf16 v[64:67], v[188:191], v[222:225], v[64:67]
	v_mfma_f32_16x16x32_bf16 v[116:119], v[184:187], v[202:205], v[116:119]
	v_mfma_f32_16x16x32_bf16 v[112:115], v[192:195], v[202:205], v[112:115]
	v_mfma_f32_16x16x32_bf16 v[100:103], v[184:187], v[210:213], v[100:103]
	v_mfma_f32_16x16x32_bf16 v[96:99], v[192:195], v[210:213], v[96:99]
	v_mfma_f32_16x16x32_bf16 v[84:87], v[184:187], v[218:221], v[84:87]
	v_mfma_f32_16x16x32_bf16 v[80:83], v[192:195], v[218:221], v[80:83]
	v_mfma_f32_16x16x32_bf16 v[68:71], v[184:187], v[226:229], v[68:71]
	v_mfma_f32_16x16x32_bf16 v[64:67], v[192:195], v[226:229], v[64:67]
	s_barrier
	s_add_i32 s62, s89, s70
	s_mov_b32 m0, s62
	ds_read_b128 v[198:201], v165 offset:49152
	ds_read_b128 v[202:205], v165 offset:50176
	ds_read_b128 v[206:209], v165 offset:51200
	ds_read_b128 v[210:213], v165 offset:52224
	ds_read_b128 v[214:217], v165 offset:53248
	ds_read_b128 v[218:221], v165 offset:54272
	ds_read_b128 v[222:225], v165 offset:55296
	ds_read_b128 v[226:229], v165 offset:56320
	global_load_lds_dwordx4 v146, s[98:99]
	s_add_i32 m0, s62, 0x2000
	s_add_u32 s34, s34, 0x40080
	s_addc_u32 s35, s35, 0
	s_add_i32 s62, s90, s70
	global_load_lds_dwordx4 v150, s[98:99]
	s_mov_b32 m0, s62
	s_nop 0
	global_load_lds_dwordx4 v146, s[34:35]
	s_add_i32 m0, s62, 0x2000
	s_nop 0
	global_load_lds_dwordx4 v150, s[34:35]
	s_mov_b32 m0, s75
	s_nop 0
	global_load_lds_dwordx4 v144, s[100:101]
	s_mov_b32 m0, s76
	s_nop 0
	global_load_lds_dwordx4 v148, s[100:101]
	s_waitcnt vmcnt(8)
	s_waitcnt lgkmcnt(0)
	s_barrier
	v_mfma_f32_16x16x32_bf16 v[60:63], v[140:143], v[198:201], v[60:63]
	v_mfma_f32_16x16x32_bf16 v[56:59], v[172:175], v[198:201], v[56:59]
	v_mfma_f32_16x16x32_bf16 v[48:51], v[140:143], v[206:209], v[48:51]
	v_mfma_f32_16x16x32_bf16 v[40:43], v[172:175], v[206:209], v[40:43]
	v_mfma_f32_16x16x32_bf16 v[32:35], v[140:143], v[214:217], v[32:35]
	v_mfma_f32_16x16x32_bf16 v[24:27], v[172:175], v[214:217], v[24:27]
	v_mfma_f32_16x16x32_bf16 v[16:19], v[140:143], v[222:225], v[16:19]
	v_mfma_f32_16x16x32_bf16 v[8:11], v[172:175], v[222:225], v[8:11]
	v_mfma_f32_16x16x32_bf16 v[60:63], v[168:171], v[202:205], v[60:63]
	v_mfma_f32_16x16x32_bf16 v[56:59], v[176:179], v[202:205], v[56:59]
	v_mfma_f32_16x16x32_bf16 v[48:51], v[168:171], v[210:213], v[48:51]
	v_mfma_f32_16x16x32_bf16 v[40:43], v[176:179], v[210:213], v[40:43]
	v_mfma_f32_16x16x32_bf16 v[32:35], v[168:171], v[218:221], v[32:35]
	v_mfma_f32_16x16x32_bf16 v[24:27], v[176:179], v[218:221], v[24:27]
	v_mfma_f32_16x16x32_bf16 v[16:19], v[168:171], v[226:229], v[16:19]
	v_mfma_f32_16x16x32_bf16 v[8:11], v[176:179], v[226:229], v[8:11]
	v_mfma_f32_16x16x32_bf16 v[52:55], v[180:183], v[198:201], v[52:55]
	v_mfma_f32_16x16x32_bf16 v[44:47], v[188:191], v[198:201], v[44:47]
	v_mfma_f32_16x16x32_bf16 v[36:39], v[180:183], v[206:209], v[36:39]
	v_mfma_f32_16x16x32_bf16 v[28:31], v[188:191], v[206:209], v[28:31]
	v_mfma_f32_16x16x32_bf16 v[20:23], v[180:183], v[214:217], v[20:23]
	v_mfma_f32_16x16x32_bf16 v[12:15], v[188:191], v[214:217], v[12:15]
	v_mfma_f32_16x16x32_bf16 v[4:7], v[180:183], v[222:225], v[4:7]
	v_mfma_f32_16x16x32_bf16 v[0:3], v[188:191], v[222:225], v[0:3]
	v_mfma_f32_16x16x32_bf16 v[52:55], v[184:187], v[202:205], v[52:55]
	v_mfma_f32_16x16x32_bf16 v[44:47], v[192:195], v[202:205], v[44:47]
	v_mfma_f32_16x16x32_bf16 v[36:39], v[184:187], v[210:213], v[36:39]
	v_mfma_f32_16x16x32_bf16 v[28:31], v[192:195], v[210:213], v[28:31]
	v_mfma_f32_16x16x32_bf16 v[20:23], v[184:187], v[218:221], v[20:23]
	v_mfma_f32_16x16x32_bf16 v[12:15], v[192:195], v[218:221], v[12:15]
	v_mfma_f32_16x16x32_bf16 v[4:7], v[184:187], v[226:229], v[4:7]
	v_mfma_f32_16x16x32_bf16 v[0:3], v[192:195], v[226:229], v[0:3]
	s_barrier
	s_add_i32 s88, s88, 2
	s_add_u32 s20, s20, 0x100
	s_addc_u32 s21, s21, 0
	s_add_u32 s86, s86, 0x100
	s_addc_u32 s87, s87, 0
	s_cmp_gt_u32 s88, 13
	s_cbranch_scc0 .LBB0_1200
	v_readlane_b32 s101, v249, 49
	s_nop 3
	s_cmp_eq_u32 s101, 0
	s_cbranch_scc1 .Ldw_done_2
	v_readlane_b32 s100, v249, 18
	s_nop 3
	s_cmp_lg_u32 s100, 0
	s_cbranch_scc1 .Ldw_ok_2
	s_add_u32 s98, s28, 0x183500
	s_addc_u32 s99, s29, 0
	v_mov_b32_e32 v251, 0
	s_mov_b32 s100, 0

; #define PG8_STAGE(bufoff, gbase, voff) do { _Pragma("unroll") for (int _i = 0; _i < 2; ++_i) \
;         __builtin_amdgcn_global_load_lds((const unsigned*)((const char*)(gbase) + (voff)[_i]), (PG8_LAS unsigned*)(lds + (bufoff) + ldsw + _i * 8192), 16, 0, 0); } while (0)
; #define PG8_LDA(dst, b, h) do { _Pragma("unroll") for (int m = 0; m < 4; ++m) _Pragma("unroll") for (int k = 0; k < 2; ++k) dst[m][k] = *(const PG8_LAS bf16x8*)(lds + PG8_SA(b, h) + aoff + m * 2048 + k * 1024); } while (0)
; #define PG8_LDB(dst, b, h) do { _Pragma("unroll") for (int n = 0; n < 2; ++n) _Pragma("unroll") for (int k = 0; k < 2; ++k) dst[n][k] = *(const PG8_LAS bf16x8*)(lds + PG8_SB(b, h) + boff + n * 2048 + k * 1024); } while (0)
; #define PG8_MMA(ai, bj, At, Bt) do { __builtin_amdgcn_s_setprio(1); _Pragma("unroll") for (int m = 0; m < 4; ++m) _Pragma("unroll") for (int n = 0; n < 2; ++n) _Pragma("unroll") for (int k = 0; k < 2; ++k) \
;         acc[ai][bj][m][n] = __builtin_amdgcn_mfma_f32_16x16x32_bf16(Bt[n][k], At[m][k], acc[ai][bj][m][n], 0, 0, 0); __builtin_amdgcn_s_setprio(0); } while (0)
; #define PG8_WAIT_V(n) asm volatile("s_waitcnt vmcnt(" #n ")" ::: "memory")
; #define PG8_WAIT_L(n) asm volatile("s_waitcnt lgkmcnt(" #n ")" ::: "memory")
; #define PG8_BAR __builtin_amdgcn_s_barrier()
; #define PG8_SCHED __builtin_amdgcn_sched_barrier(0)
; template <class Epi, class Sched, bool ALIGN_EPI = false, bool SP2 = false>
; __device__ __forceinline__ void gemm_phase(PG8_LAS unsigned char* lds, const Gemm g, const Sched& S, const Epi& E) {
;     ...
;             PG8_LDB(B0, 0, 0); PG8_LDB(B1, 0, 1); PG8_SCHED; PG8_LDA(At, 0, 0); PG8_STAGE(PG8_SA(1, 1), a1 + hstep, voffA);
;             PG8_WAIT_V(8); PG8_WAIT_L(0); PG8_BAR; PG8_MMA(0, 0, At, B0); PG8_MMA(0, 1, At, B1); PG8_BAR; PG8_SCHED;
;             PG8_LDA(At, 0, 1); PG8_STAGE(PG8_SB(0, 0), b2, voffB); PG8_STAGE(PG8_SB(0, 1), b2 + hstep, voffB); PG8_STAGE(PG8_SA(0, 0), a2, voffA);
;             PG8_WAIT_V(8); PG8_WAIT_L(0); PG8_BAR; PG8_MMA(1, 0, At, B0); PG8_MMA(1, 1, At, B1); PG8_BAR; PG8_SCHED;
.LBB0_1740:
	ds_read_b128 v[154:157], v150
	ds_read_b128 v[158:161], v150 offset:1024
	ds_read_b128 v[162:165], v150 offset:2048
	ds_read_b128 v[166:169], v150 offset:3072
	ds_read_b128 v[170:173], v151
	ds_read_b128 v[174:177], v151 offset:1024
	ds_read_b128 v[178:181], v151 offset:2048
	ds_read_b128 v[182:185], v151 offset:3072
	s_add_u32 s38, s20, 0xfffc0080
	s_addc_u32 s39, s21, -1
	s_cmp_eq_u32 s67, 12
	s_cselect_b32 s43, s15, s39
	s_cselect_b32 s42, s63, s38
	s_cselect_b32 s39, s13, s66
	s_cselect_b32 s38, s64, s65
	s_add_i32 m0, s35, 0xc000
	ds_read_b128 v[186:189], v152
	ds_read_b128 v[190:193], v152 offset:1024
	ds_read_b128 v[198:201], v152 offset:2048
	ds_read_b128 v[202:205], v152 offset:3072
	ds_read_b128 v[206:209], v152 offset:4096
	ds_read_b128 v[210:213], v152 offset:5120
	ds_read_b128 v[214:217], v152 offset:6144
	ds_read_b128 v[218:221], v152 offset:7168
	global_load_lds_dwordx4 v136, s[20:21]
	s_add_i32 m0, s35, 0xe000
	s_nop 0
	global_load_lds_dwordx4 v138, s[20:21]
	s_waitcnt vmcnt(8)
	s_waitcnt lgkmcnt(0)
	s_barrier
	v_mfma_f32_16x16x32_bf16 v[124:127], v[154:157], v[186:189], v[124:127]
	v_mfma_f32_16x16x32_bf16 v[116:119], v[162:165], v[186:189], v[116:119]
	v_mfma_f32_16x16x32_bf16 v[108:111], v[154:157], v[198:201], v[108:111]
	v_mfma_f32_16x16x32_bf16 v[100:103], v[162:165], v[198:201], v[100:103]
	v_mfma_f32_16x16x32_bf16 v[92:95], v[154:157], v[206:209], v[92:95]
	v_mfma_f32_16x16x32_bf16 v[84:87], v[162:165], v[206:209], v[84:87]
	v_mfma_f32_16x16x32_bf16 v[76:79], v[154:157], v[214:217], v[76:79]
	v_mfma_f32_16x16x32_bf16 v[68:71], v[162:165], v[214:217], v[68:71]
	v_mfma_f32_16x16x32_bf16 v[124:127], v[158:161], v[190:193], v[124:127]
	v_mfma_f32_16x16x32_bf16 v[116:119], v[166:169], v[190:193], v[116:119]
	v_mfma_f32_16x16x32_bf16 v[108:111], v[158:161], v[202:205], v[108:111]
	v_mfma_f32_16x16x32_bf16 v[100:103], v[166:169], v[202:205], v[100:103]
	v_mfma_f32_16x16x32_bf16 v[92:95], v[158:161], v[210:213], v[92:95]
	v_mfma_f32_16x16x32_bf16 v[84:87], v[166:169], v[210:213], v[84:87]
	v_mfma_f32_16x16x32_bf16 v[76:79], v[158:161], v[218:221], v[76:79]
	v_mfma_f32_16x16x32_bf16 v[68:71], v[166:169], v[218:221], v[68:71]
	v_mfma_f32_16x16x32_bf16 v[120:123], v[170:173], v[186:189], v[120:123]
	v_mfma_f32_16x16x32_bf16 v[112:115], v[178:181], v[186:189], v[112:115]
	v_mfma_f32_16x16x32_bf16 v[104:107], v[170:173], v[198:201], v[104:107]
	v_mfma_f32_16x16x32_bf16 v[96:99], v[178:181], v[198:201], v[96:99]
	v_mfma_f32_16x16x32_bf16 v[88:91], v[170:173], v[206:209], v[88:91]
	v_mfma_f32_16x16x32_bf16 v[80:83], v[178:181], v[206:209], v[80:83]
	v_mfma_f32_16x16x32_bf16 v[72:75], v[170:173], v[214:217], v[72:75]
	v_mfma_f32_16x16x32_bf16 v[64:67], v[178:181], v[214:217], v[64:67]
	v_mfma_f32_16x16x32_bf16 v[120:123], v[174:177], v[190:193], v[120:123]
	v_mfma_f32_16x16x32_bf16 v[112:115], v[182:185], v[190:193], v[112:115]
	v_mfma_f32_16x16x32_bf16 v[104:107], v[174:177], v[202:205], v[104:107]
	v_mfma_f32_16x16x32_bf16 v[96:99], v[182:185], v[202:205], v[96:99]
	v_mfma_f32_16x16x32_bf16 v[88:91], v[174:177], v[210:213], v[88:91]
	v_mfma_f32_16x16x32_bf16 v[80:83], v[182:185], v[210:213], v[80:83]
	v_mfma_f32_16x16x32_bf16 v[72:75], v[174:177], v[218:221], v[72:75]
	v_mfma_f32_16x16x32_bf16 v[64:67], v[182:185], v[218:221], v[64:67]
	s_barrier
	s_add_i32 s68, s58, s50
	s_add_u32 s98, s38, s8
	s_addc_u32 s99, s39, s9
	s_add_u32 s100, s42, s8
	s_addc_u32 s101, s43, s9
	s_mov_b32 m0, s68
	ds_read_b128 v[186:189], v152 offset:16384
	ds_read_b128 v[190:193], v152 offset:17408
	ds_read_b128 v[198:201], v152 offset:18432
	ds_read_b128 v[202:205], v152 offset:19456
	ds_read_b128 v[206:209], v152 offset:20480
	ds_read_b128 v[210:213], v152 offset:21504
	ds_read_b128 v[214:217], v152 offset:22528
	ds_read_b128 v[218:221], v152 offset:23552
	global_load_lds_dwordx4 v132, s[38:39]
	s_add_i32 m0, s68, 0x2000
	s_add_u32 s68, s38, 0x40000
	s_addc_u32 s69, s39, 0
	s_add_i32 s70, s59, s50
	global_load_lds_dwordx4 v128, s[38:39]
	s_mov_b32 m0, s70
	s_nop 0
	global_load_lds_dwordx4 v132, s[68:69]
	s_add_i32 m0, s70, 0x2000
	s_nop 0
	global_load_lds_dwordx4 v128, s[68:69]
	s_mov_b32 m0, s35
	s_nop 0
	global_load_lds_dwordx4 v134, s[42:43]
	s_mov_b32 m0, s52
	s_nop 0
	global_load_lds_dwordx4 v130, s[42:43]
	s_waitcnt vmcnt(8)
	s_waitcnt lgkmcnt(0)
	s_barrier
	v_mfma_f32_16x16x32_bf16 v[60:63], v[154:157], v[186:189], v[60:63]
	v_mfma_f32_16x16x32_bf16 v[52:55], v[162:165], v[186:189], v[52:55]
	v_mfma_f32_16x16x32_bf16 v[44:47], v[154:157], v[198:201], v[44:47]
	v_mfma_f32_16x16x32_bf16 v[36:39], v[162:165], v[198:201], v[36:39]
	v_mfma_f32_16x16x32_bf16 v[28:31], v[154:157], v[206:209], v[28:31]
	v_mfma_f32_16x16x32_bf16 v[20:23], v[162:165], v[206:209], v[20:23]
	v_mfma_f32_16x16x32_bf16 v[12:15], v[154:157], v[214:217], v[12:15]
	v_mfma_f32_16x16x32_bf16 v[4:7], v[162:165], v[214:217], v[4:7]
	v_mfma_f32_16x16x32_bf16 v[60:63], v[158:161], v[190:193], v[60:63]
	v_mfma_f32_16x16x32_bf16 v[52:55], v[166:169], v[190:193], v[52:55]
	v_mfma_f32_16x16x32_bf16 v[44:47], v[158:161], v[202:205], v[44:47]
	v_mfma_f32_16x16x32_bf16 v[36:39], v[166:169], v[202:205], v[36:39]
	v_mfma_f32_16x16x32_bf16 v[28:31], v[158:161], v[210:213], v[28:31]
	v_mfma_f32_16x16x32_bf16 v[20:23], v[166:169], v[210:213], v[20:23]
	v_mfma_f32_16x16x32_bf16 v[12:15], v[158:161], v[218:221], v[12:15]
	v_mfma_f32_16x16x32_bf16 v[4:7], v[166:169], v[218:221], v[4:7]
	v_mfma_f32_16x16x32_bf16 v[56:59], v[170:173], v[186:189], v[56:59]
	v_mfma_f32_16x16x32_bf16 v[48:51], v[178:181], v[186:189], v[48:51]
	v_mfma_f32_16x16x32_bf16 v[40:43], v[170:173], v[198:201], v[40:43]
	v_mfma_f32_16x16x32_bf16 v[32:35], v[178:181], v[198:201], v[32:35]
	v_mfma_f32_16x16x32_bf16 v[24:27], v[170:173], v[206:209], v[24:27]
	v_mfma_f32_16x16x32_bf16 v[16:19], v[178:181], v[206:209], v[16:19]
	v_mfma_f32_16x16x32_bf16 v[8:11], v[170:173], v[214:217], v[8:11]
	v_mfma_f32_16x16x32_bf16 v[0:3], v[178:181], v[214:217], v[0:3]
	v_mfma_f32_16x16x32_bf16 v[56:59], v[174:177], v[190:193], v[56:59]
	v_mfma_f32_16x16x32_bf16 v[48:51], v[182:185], v[190:193], v[48:51]
	v_mfma_f32_16x16x32_bf16 v[40:43], v[174:177], v[202:205], v[40:43]
	v_mfma_f32_16x16x32_bf16 v[32:35], v[182:185], v[202:205], v[32:35]
	v_mfma_f32_16x16x32_bf16 v[24:27], v[174:177], v[210:213], v[24:27]
	v_mfma_f32_16x16x32_bf16 v[16:19], v[182:185], v[210:213], v[16:19]
	v_mfma_f32_16x16x32_bf16 v[8:11], v[174:177], v[218:221], v[8:11]
	v_mfma_f32_16x16x32_bf16 v[0:3], v[182:185], v[218:221], v[0:3]
	s_barrier
; #define PG8_STAGE(bufoff, gbase, voff) do { _Pragma("unroll") for (int _i = 0; _i < 2; ++_i) \
;         __builtin_amdgcn_global_load_lds((const unsigned*)((const char*)(gbase) + (voff)[_i]), (PG8_LAS unsigned*)(lds + (bufoff) + ldsw + _i * 8192), 16, 0, 0); } while (0)
; #define PG8_LDA(dst, b, h) do { _Pragma("unroll") for (int m = 0; m < 4; ++m) _Pragma("unroll") for (int k = 0; k < 2; ++k) dst[m][k] = *(const PG8_LAS bf16x8*)(lds + PG8_SA(b, h) + aoff + m * 2048 + k * 1024); } while (0)
; #define PG8_LDB(dst, b, h) do { _Pragma("unroll") for (int n = 0; n < 2; ++n) _Pragma("unroll") for (int k = 0; k < 2; ++k) dst[n][k] = *(const PG8_LAS bf16x8*)(lds + PG8_SB(b, h) + boff + n * 2048 + k * 1024); } while (0)
; #define PG8_MMA(ai, bj, At, Bt) do { __builtin_amdgcn_s_setprio(1); _Pragma("unroll") for (int m = 0; m < 4; ++m) _Pragma("unroll") for (int n = 0; n < 2; ++n) _Pragma("unroll") for (int k = 0; k < 2; ++k) \
;         acc[ai][bj][m][n] = __builtin_amdgcn_mfma_f32_16x16x32_bf16(Bt[n][k], At[m][k], acc[ai][bj][m][n], 0, 0, 0); __builtin_amdgcn_s_setprio(0); } while (0)
; #define PG8_WAIT_V(n) asm volatile("s_waitcnt vmcnt(" #n ")" ::: "memory")
; #define PG8_WAIT_L(n) asm volatile("s_waitcnt lgkmcnt(" #n ")" ::: "memory")
; #define PG8_BAR __builtin_amdgcn_s_barrier()
; #define PG8_SCHED __builtin_amdgcn_sched_barrier(0)
; template <class Epi, class Sched, bool ALIGN_EPI = false, bool SP2 = false>
; __device__ __forceinline__ void gemm_phase(PG8_LAS unsigned char* lds, const Gemm g, const Sched& S, const Epi& E) {
;     ...
;         for (int t = 0; t < nt; t += 2) {
;     ...
;             PG8_LDB(B0, 1, 0); PG8_LDB(B1, 1, 1); PG8_SCHED; PG8_LDA(At, 1, 0); PG8_STAGE(PG8_SA(0, 1), a2 + hstep, voffA);
;             PG8_WAIT_V(8); PG8_WAIT_L(0); PG8_BAR; PG8_MMA(0, 0, At, B0); PG8_MMA(0, 1, At, B1); PG8_BAR; PG8_SCHED;
;             PG8_LDA(At, 1, 1); PG8_STAGE(PG8_SB(1, 0), b3, voffB); PG8_STAGE(PG8_SB(1, 1), b3 + hstep, voffB); PG8_STAGE(PG8_SA(1, 0), a3, voffA);
;             PG8_WAIT_V(8); PG8_WAIT_L(0); PG8_BAR; PG8_MMA(1, 0, At, B0); PG8_MMA(1, 1, At, B1); PG8_BAR; PG8_SCHED;
	s_add_i32 s68, 0, 0x18000
	v_add_u32_e32 v153, s68, v147
	s_add_i32 s69, 0, 0x1c000
	ds_read_b128 v[154:157], v153
	ds_read_b128 v[158:161], v153 offset:1024
	ds_read_b128 v[162:165], v153 offset:2048
	ds_read_b128 v[166:169], v153 offset:3072
	v_add_u32_e32 v153, s69, v147
	ds_read_b128 v[170:173], v153
	ds_read_b128 v[174:177], v153 offset:1024
	ds_read_b128 v[178:181], v153 offset:2048
	ds_read_b128 v[182:185], v153 offset:3072
	s_add_u32 s42, s42, 0x40000
	s_addc_u32 s43, s43, 0
	s_mov_b32 m0, s53
	ds_read_b128 v[186:189], v152 offset:32768
	ds_read_b128 v[190:193], v152 offset:33792
	ds_read_b128 v[198:201], v152 offset:34816
	ds_read_b128 v[202:205], v152 offset:35840
	ds_read_b128 v[206:209], v152 offset:36864
	ds_read_b128 v[210:213], v152 offset:37888
	ds_read_b128 v[214:217], v152 offset:38912
	ds_read_b128 v[218:221], v152 offset:39936
	global_load_lds_dwordx4 v134, s[42:43]
	s_mov_b32 m0, s54
	s_nop 0
	global_load_lds_dwordx4 v130, s[42:43]
	s_waitcnt vmcnt(8)
	s_waitcnt lgkmcnt(0)
	s_barrier
	v_mfma_f32_16x16x32_bf16 v[124:127], v[154:157], v[186:189], v[124:127]
	v_mfma_f32_16x16x32_bf16 v[116:119], v[162:165], v[186:189], v[116:119]
	v_mfma_f32_16x16x32_bf16 v[108:111], v[154:157], v[198:201], v[108:111]
	v_mfma_f32_16x16x32_bf16 v[100:103], v[162:165], v[198:201], v[100:103]
	v_mfma_f32_16x16x32_bf16 v[92:95], v[154:157], v[206:209], v[92:95]
	v_mfma_f32_16x16x32_bf16 v[84:87], v[162:165], v[206:209], v[84:87]
	v_mfma_f32_16x16x32_bf16 v[76:79], v[154:157], v[214:217], v[76:79]
	v_mfma_f32_16x16x32_bf16 v[68:71], v[162:165], v[214:217], v[68:71]
	v_mfma_f32_16x16x32_bf16 v[124:127], v[158:161], v[190:193], v[124:127]
	v_mfma_f32_16x16x32_bf16 v[116:119], v[166:169], v[190:193], v[116:119]
	v_mfma_f32_16x16x32_bf16 v[108:111], v[158:161], v[202:205], v[108:111]
	v_mfma_f32_16x16x32_bf16 v[100:103], v[166:169], v[202:205], v[100:103]
	v_mfma_f32_16x16x32_bf16 v[92:95], v[158:161], v[210:213], v[92:95]
	v_mfma_f32_16x16x32_bf16 v[84:87], v[166:169], v[210:213], v[84:87]
	v_mfma_f32_16x16x32_bf16 v[76:79], v[158:161], v[218:221], v[76:79]
	v_mfma_f32_16x16x32_bf16 v[68:71], v[166:169], v[218:221], v[68:71]
	v_mfma_f32_16x16x32_bf16 v[120:123], v[170:173], v[186:189], v[120:123]
	v_mfma_f32_16x16x32_bf16 v[112:115], v[178:181], v[186:189], v[112:115]
	v_mfma_f32_16x16x32_bf16 v[104:107], v[170:173], v[198:201], v[104:107]
	v_mfma_f32_16x16x32_bf16 v[96:99], v[178:181], v[198:201], v[96:99]
	v_mfma_f32_16x16x32_bf16 v[88:91], v[170:173], v[206:209], v[88:91]
	v_mfma_f32_16x16x32_bf16 v[80:83], v[178:181], v[206:209], v[80:83]
	v_mfma_f32_16x16x32_bf16 v[72:75], v[170:173], v[214:217], v[72:75]
	v_mfma_f32_16x16x32_bf16 v[64:67], v[178:181], v[214:217], v[64:67]
	v_mfma_f32_16x16x32_bf16 v[120:123], v[174:177], v[190:193], v[120:123]
	v_mfma_f32_16x16x32_bf16 v[112:115], v[182:185], v[190:193], v[112:115]
	v_mfma_f32_16x16x32_bf16 v[104:107], v[174:177], v[202:205], v[104:107]
	v_mfma_f32_16x16x32_bf16 v[96:99], v[182:185], v[202:205], v[96:99]
	v_mfma_f32_16x16x32_bf16 v[88:91], v[174:177], v[210:213], v[88:91]
	v_mfma_f32_16x16x32_bf16 v[80:83], v[182:185], v[210:213], v[80:83]
	v_mfma_f32_16x16x32_bf16 v[72:75], v[174:177], v[218:221], v[72:75]
	v_mfma_f32_16x16x32_bf16 v[64:67], v[182:185], v[218:221], v[64:67]
	s_barrier
	s_add_i32 s42, s68, s50
	s_mov_b32 m0, s42
	ds_read_b128 v[186:189], v152 offset:49152
	ds_read_b128 v[190:193], v152 offset:50176
	ds_read_b128 v[198:201], v152 offset:51200
	ds_read_b128 v[202:205], v152 offset:52224
	ds_read_b128 v[206:209], v152 offset:53248
	ds_read_b128 v[210:213], v152 offset:54272
	ds_read_b128 v[214:217], v152 offset:55296
	ds_read_b128 v[218:221], v152 offset:56320
	global_load_lds_dwordx4 v132, s[98:99]
	s_add_i32 m0, s42, 0x2000
	s_add_u32 s38, s38, 0x40080
	s_addc_u32 s39, s39, 0
	s_add_i32 s42, s69, s50
	global_load_lds_dwordx4 v128, s[98:99]
	s_mov_b32 m0, s42
	s_nop 0
	global_load_lds_dwordx4 v132, s[38:39]
	s_add_i32 m0, s42, 0x2000
	s_nop 0
	global_load_lds_dwordx4 v128, s[38:39]
	s_mov_b32 m0, s56
	s_nop 0
	global_load_lds_dwordx4 v134, s[100:101]
	s_mov_b32 m0, s57
	s_nop 0
	global_load_lds_dwordx4 v130, s[100:101]
	s_waitcnt vmcnt(8)
	s_waitcnt lgkmcnt(0)
	s_barrier
	v_mfma_f32_16x16x32_bf16 v[60:63], v[154:157], v[186:189], v[60:63]
	v_mfma_f32_16x16x32_bf16 v[52:55], v[162:165], v[186:189], v[52:55]
	v_mfma_f32_16x16x32_bf16 v[44:47], v[154:157], v[198:201], v[44:47]
	v_mfma_f32_16x16x32_bf16 v[36:39], v[162:165], v[198:201], v[36:39]
	v_mfma_f32_16x16x32_bf16 v[28:31], v[154:157], v[206:209], v[28:31]
	v_mfma_f32_16x16x32_bf16 v[20:23], v[162:165], v[206:209], v[20:23]
	v_mfma_f32_16x16x32_bf16 v[12:15], v[154:157], v[214:217], v[12:15]
	v_mfma_f32_16x16x32_bf16 v[4:7], v[162:165], v[214:217], v[4:7]
	v_mfma_f32_16x16x32_bf16 v[60:63], v[158:161], v[190:193], v[60:63]
	v_mfma_f32_16x16x32_bf16 v[52:55], v[166:169], v[190:193], v[52:55]
	v_mfma_f32_16x16x32_bf16 v[44:47], v[158:161], v[202:205], v[44:47]
	v_mfma_f32_16x16x32_bf16 v[36:39], v[166:169], v[202:205], v[36:39]
	v_mfma_f32_16x16x32_bf16 v[28:31], v[158:161], v[210:213], v[28:31]
	v_mfma_f32_16x16x32_bf16 v[20:23], v[166:169], v[210:213], v[20:23]
	v_mfma_f32_16x16x32_bf16 v[12:15], v[158:161], v[218:221], v[12:15]
	v_mfma_f32_16x16x32_bf16 v[4:7], v[166:169], v[218:221], v[4:7]
	v_mfma_f32_16x16x32_bf16 v[56:59], v[170:173], v[186:189], v[56:59]
	v_mfma_f32_16x16x32_bf16 v[48:51], v[178:181], v[186:189], v[48:51]
	v_mfma_f32_16x16x32_bf16 v[40:43], v[170:173], v[198:201], v[40:43]
	v_mfma_f32_16x16x32_bf16 v[32:35], v[178:181], v[198:201], v[32:35]
	v_mfma_f32_16x16x32_bf16 v[24:27], v[170:173], v[206:209], v[24:27]
	v_mfma_f32_16x16x32_bf16 v[16:19], v[178:181], v[206:209], v[16:19]
	v_mfma_f32_16x16x32_bf16 v[8:11], v[170:173], v[214:217], v[8:11]
	v_mfma_f32_16x16x32_bf16 v[0:3], v[178:181], v[214:217], v[0:3]
	v_mfma_f32_16x16x32_bf16 v[56:59], v[174:177], v[190:193], v[56:59]
	v_mfma_f32_16x16x32_bf16 v[48:51], v[182:185], v[190:193], v[48:51]
	v_mfma_f32_16x16x32_bf16 v[40:43], v[174:177], v[202:205], v[40:43]
	v_mfma_f32_16x16x32_bf16 v[32:35], v[182:185], v[202:205], v[32:35]
	v_mfma_f32_16x16x32_bf16 v[24:27], v[174:177], v[210:213], v[24:27]
	v_mfma_f32_16x16x32_bf16 v[16:19], v[182:185], v[210:213], v[16:19]
	v_mfma_f32_16x16x32_bf16 v[8:11], v[174:177], v[218:221], v[8:11]
	v_mfma_f32_16x16x32_bf16 v[0:3], v[182:185], v[218:221], v[0:3]
	s_barrier
	s_add_i32 s67, s67, 2
	s_add_u32 s20, s20, 0x100
	s_addc_u32 s21, s21, 0
	s_add_u32 s65, s65, 0x100
	s_addc_u32 s66, s66, 0
	s_cmp_gt_u32 s67, 13
	s_cbranch_scc0 .LBB0_1740
	v_readlane_b32 s101, v249, 49
	s_nop 3
	s_cmp_eq_u32 s101, 0
	s_cbranch_scc1 .Ldw_done_3
	v_readlane_b32 s100, v249, 18
	s_nop 3
	s_cmp_lg_u32 s100, 0
	s_cbranch_scc1 .Ldw_ok_3
	s_add_u32 s98, s28, 0x183500
	s_addc_u32 s99, s29, 0
	v_mov_b32_e32 v251, 0
	s_mov_b32 s100, 0
